# forget-gate projection in the row pass: LDS weight reads issued four deep instead of one at a time
# speedup vs baseline: 1.0037x; 1.0037x over previous
; __device__ __forceinline__ unsigned pk2(float lo, float hi) { return f2bf(lo) | (f2bf(hi) << 16); }
; __device__ __forceinline__ void row_process(const RowArgs& R, int m, int lane, const RowRaw& q, const float (&gp)[2][8], const float (&gn)[2][8], const f32x4 bf, const LAS f32x4* afl) {
;     ...
;     if (R.gnext) {
;         float ss = 0.f;
; #pragma unroll
;         for (int j = 0; j < 2; ++j)
; #pragma unroll
;             for (int c = 0; c < 8; ++c) ss += v[j][c] * v[j][c];
;         const float r2 = 1.0f / sqrtf(wave_sum(ss) * (1.0f / DM) + EPS);
;         float un[2][8];
; #pragma unroll
;         for (int j = 0; j < 2; ++j) {
; #pragma unroll
;             for (int c = 0; c < 8; ++c) un[j][c] = (v[j][c] * r2) * gn[j][c];
;             u32x4 w; w.x = pk2(un[j][0], un[j][1]); w.y = pk2(un[j][2], un[j][3]); w.z = pk2(un[j][4], un[j][5]); w.w = pk2(un[j][6], un[j][7]);
;             *(u32x4*)(R.U + off + 512 * j) = w;
;         }
.LBB0_268:
	s_and_b64 vcc, exec, s[6:7]
	s_cbranch_vccnz .LBB0_273
	v_pk_mul_f32 v[150:151], v[132:133], v[132:133]
	v_pk_mul_f32 v[152:153], v[136:137], v[136:137]
	v_pk_mul_f32 v[154:155], v[134:135], v[134:135]
	v_add_f32_e32 v0, v150, v152
	v_add_f32_e32 v0, v0, v151
	v_add_f32_e32 v0, v0, v153
	v_pk_mul_f32 v[156:157], v[138:139], v[138:139]
	v_add_f32_e32 v0, v0, v154
	v_add_f32_e32 v0, v0, v156
	v_add_f32_e32 v0, v0, v155
	v_pk_mul_f32 v[158:159], v[128:129], v[128:129]
	v_add_f32_e32 v0, v0, v157
	v_add_f32_e32 v0, v0, v158
	v_pk_mul_f32 v[160:161], v[130:131], v[130:131]
	v_add_f32_e32 v0, v0, v159
	v_add_f32_e32 v0, v0, v160
	v_pk_mul_f32 v[162:163], v[124:125], v[124:125]
	v_add_f32_e32 v0, v0, v161
	v_add_f32_e32 v0, v0, v162
	v_pk_mul_f32 v[164:165], v[126:127], v[126:127]
	v_add_f32_e32 v0, v0, v163
	v_add_f32_e32 v0, v0, v164
	v_add_f32_e32 v0, v0, v165
	s_nop 1
	v_add_f32_dpp v0, v0, v0 quad_perm:[1,0,3,2] row_mask:0xf bank_mask:0xf bound_ctrl:1
	s_nop 1
	v_add_f32_dpp v0, v0, v0 quad_perm:[2,3,0,1] row_mask:0xf bank_mask:0xf bound_ctrl:1
	s_nop 1
	v_add_f32_dpp v0, v0, v0 row_half_mirror row_mask:0xf bank_mask:0xf bound_ctrl:1
	s_nop 1
	v_add_f32_dpp v0, v0, v0 row_mirror row_mask:0xf bank_mask:0xf bound_ctrl:1
	s_nop 0
	v_readlane_b32 s1, v0, 16
	v_readlane_b32 s3, v0, 48
	v_readlane_b32 s16, v0, 0
	v_readlane_b32 s17, v0, 32
	v_mov_b32_e32 v150, s1
	v_mov_b32_e32 v151, s3
	v_pk_add_f32 v[150:151], s[16:17], v[150:151]
	s_nop 0
	v_add_f32_e32 v0, v150, v151
	v_fmamk_f32 v0, v0, 0x3a800000, v229
	v_mul_f32_e32 v143, 0x4f800000, v0
	v_cmp_gt_f32_e32 vcc, s59, v0
	s_nop 1
	v_cndmask_b32_e32 v0, v0, v143, vcc
	v_sqrt_f32_e32 v143, v0
	s_nop 0
	v_add_u32_e32 v150, -1, v143
	v_fma_f32 v151, -v150, v143, v0
	v_cmp_ge_f32_e64 s[16:17], 0, v151
	v_add_u32_e32 v151, 1, v143
	s_nop 0
	v_cndmask_b32_e64 v150, v143, v150, s[16:17]
	v_fma_f32 v143, -v151, v143, v0
	v_cmp_lt_f32_e64 s[16:17], 0, v143
	s_nop 1
	v_cndmask_b32_e64 v143, v150, v151, s[16:17]
	v_mul_f32_e32 v150, 0x37800000, v143
	v_cndmask_b32_e32 v143, v143, v150, vcc
	v_cmp_class_f32_e32 vcc, v0, v230
	s_nop 1
	v_cndmask_b32_e32 v0, v143, v0, vcc
	v_div_scale_f32 v143, s[16:17], v0, v0, 1.0
	v_rcp_f32_e32 v150, v143
	s_nop 0
	v_fma_f32 v151, -v143, v150, 1.0
	v_fmac_f32_e32 v150, v151, v150
	v_div_scale_f32 v151, vcc, 1.0, v0, 1.0
	v_mul_f32_e32 v152, v151, v150
	v_fma_f32 v153, -v143, v152, v151
	v_fmac_f32_e32 v152, v153, v150
	v_fma_f32 v143, -v143, v152, v151
	v_div_fmas_f32 v143, v143, v150, v152
	v_div_fixup_f32 v0, v143, v0, 1.0
	v_pk_mul_f32 v[132:133], v[132:133], v[0:1] op_sel_hi:[1,0]
	s_and_b64 vcc, exec, s[8:9]
	v_pk_mul_f32 v[152:153], v[2:3], v[132:133]
	v_pk_mul_f32 v[132:133], v[136:137], v[0:1] op_sel_hi:[1,0]
	v_bfe_u32 v143, v152, 16, 1
	v_pk_mul_f32 v[150:151], v[144:145], v[132:133]
	v_pk_mul_f32 v[132:133], v[134:135], v[0:1] op_sel_hi:[1,0]
	v_bfe_u32 v154, v153, 16, 1
	v_pk_mul_f32 v[136:137], v[8:9], v[132:133]
	v_pk_mul_f32 v[132:133], v[138:139], v[0:1] op_sel_hi:[1,0]
	v_bfe_u32 v155, v136, 16, 1
	v_pk_mul_f32 v[134:135], v[4:5], v[132:133]
	v_bfe_u32 v156, v137, 16, 1
	v_bfe_u32 v132, v135, 16, 1
	v_bfe_u32 v133, v134, 16, 1
	v_add3_u32 v156, v137, v156, s53
	v_add3_u32 v155, v136, v155, s53
	v_add3_u32 v133, v134, v133, s53
	v_add3_u32 v132, v135, v132, s53
	v_lshrrev_b32_e32 v155, 16, v155
	v_lshrrev_b32_e32 v156, 16, v156
	v_and_or_b32 v157, v132, s56, v156
	v_and_or_b32 v156, v133, s56, v155
	v_mov_b32_e32 v133, v130
	v_mov_b32_e32 v130, v129
	v_mov_b32_e32 v132, v128
	v_pk_mul_f32 v[128:129], v[130:131], v[0:1] op_sel_hi:[1,0]
	v_bfe_u32 v138, v151, 16, 1
	v_bfe_u32 v139, v150, 16, 1
	v_add3_u32 v154, v153, v154, s53
	v_add3_u32 v143, v152, v143, s53
	v_pk_mul_f32 v[130:131], v[10:11], v[128:129]
	v_mov_b32_e32 v128, v124
	v_mov_b32_e32 v129, v126
	v_add3_u32 v139, v150, v139, s53
	v_add3_u32 v138, v151, v138, s53
	v_lshrrev_b32_e32 v143, 16, v143
	v_lshrrev_b32_e32 v154, 16, v154
	v_pk_mul_f32 v[132:133], v[132:133], v[0:1] op_sel_hi:[1,0]
	v_pk_mul_f32 v[128:129], v[128:129], v[0:1] op_sel_hi:[1,0]
	v_mov_b32_e32 v126, v125
	v_and_or_b32 v155, v138, s56, v154
	v_and_or_b32 v154, v139, s56, v143
	v_lshl_add_u64 v[138:139], v[148:149], 1, s[24:25]
	v_pk_mul_f32 v[132:133], v[16:17], v[132:133]
	v_pk_mul_f32 v[128:129], v[24:25], v[128:129]
	v_pk_mul_f32 v[124:125], v[126:127], v[0:1] op_sel_hi:[1,0]
	global_store_dwordx4 v[138:139], v[154:157], off
	v_pk_mul_f32 v[124:125], v[18:19], v[124:125]
	v_bfe_u32 v148, v132, 16, 1
	v_bfe_u32 v149, v133, 16, 1
	v_bfe_u32 v154, v128, 16, 1
	v_bfe_u32 v155, v129, 16, 1
	v_bfe_u32 v0, v125, 16, 1
	v_bfe_u32 v126, v124, 16, 1
	v_bfe_u32 v127, v131, 16, 1
	v_bfe_u32 v143, v130, 16, 1
	v_add3_u32 v155, v129, v155, s53
	v_add3_u32 v154, v128, v154, s53
	v_add3_u32 v149, v133, v149, s53
	v_add3_u32 v148, v132, v148, s53
	v_add3_u32 v143, v130, v143, s53
	v_add3_u32 v127, v131, v127, s53
	v_add3_u32 v126, v124, v126, s53
	v_add3_u32 v0, v125, v0, s53
	v_lshrrev_b32_e32 v148, 16, v148
	v_lshrrev_b32_e32 v149, 16, v149
	v_lshrrev_b32_e32 v154, 16, v154
	v_lshrrev_b32_e32 v155, 16, v155
	v_and_or_b32 v157, v0, s56, v155
	v_and_or_b32 v156, v126, s56, v154
	v_and_or_b32 v155, v127, s56, v149
	v_and_or_b32 v154, v143, s56, v148
	global_store_dwordx4 v[138:139], v[154:157], off offset:1024
	s_cbranch_vccnz .LBB0_273
; __device__ __forceinline__ void row_process(const RowArgs& R, int m, int lane, const RowRaw& q, const float (&gp)[2][8], const float (&gn)[2][8], const f32x4 bf, const LAS f32x4* afl) {
;     ...
;         if (R.AF) {
;             f32x4 acc = {0.f, 0.f, 0.f, 0.f};
; #pragma unroll
;             for (int j = 0; j < 2; ++j)
; #pragma unroll
;                 for (int c = 0; c < 8; ++c) acc = acc + un[j][c] * afl[(8 * j + c) * 64 + lane];
;             acc[0] = wave_sum(acc[0]); acc[1] = wave_sum(acc[1]); acc[2] = wave_sum(acc[2]); acc[3] = wave_sum(acc[3]);
	ds_read_b128 v[36:39], v30
	ds_read_b128 v[40:43], v30 offset:1024
	ds_read_b128 v[52:55], v30 offset:2048
	ds_read_b128 v[56:59], v30 offset:3072
	s_waitcnt lgkmcnt(3)
	v_pk_fma_f32 v[126:127], v[152:153], v[36:37], 0 op_sel_hi:[0,1,0]
	v_pk_fma_f32 v[138:139], v[152:153], v[38:39], 0 op_sel_hi:[0,1,0]
	ds_read_b128 v[36:39], v30 offset:4096
	s_waitcnt lgkmcnt(3)
	v_pk_fma_f32 v[138:139], v[150:151], v[42:43], v[138:139] op_sel_hi:[0,1,1]
	v_pk_fma_f32 v[126:127], v[150:151], v[40:41], v[126:127] op_sel_hi:[0,1,1]
	ds_read_b128 v[40:43], v30 offset:5120
	s_waitcnt lgkmcnt(3)
	v_pk_fma_f32 v[138:139], v[152:153], v[54:55], v[138:139] op_sel:[1,0,0]
	v_pk_fma_f32 v[126:127], v[152:153], v[52:53], v[126:127] op_sel:[1,0,0]
	ds_read_b128 v[52:55], v30 offset:6144
	s_waitcnt lgkmcnt(3)
	v_pk_fma_f32 v[138:139], v[150:151], v[58:59], v[138:139] op_sel:[1,0,0]
	v_pk_fma_f32 v[126:127], v[150:151], v[56:57], v[126:127] op_sel:[1,0,0]
	ds_read_b128 v[56:59], v30 offset:7168
	s_waitcnt lgkmcnt(3)
	v_pk_fma_f32 v[138:139], v[136:137], v[38:39], v[138:139] op_sel_hi:[0,1,1]
	v_pk_fma_f32 v[126:127], v[136:137], v[36:37], v[126:127] op_sel_hi:[0,1,1]
	ds_read_b128 v[36:39], v30 offset:8192
	s_waitcnt lgkmcnt(3)
	v_pk_fma_f32 v[138:139], v[134:135], v[42:43], v[138:139] op_sel_hi:[0,1,1]
	v_pk_fma_f32 v[126:127], v[134:135], v[40:41], v[126:127] op_sel_hi:[0,1,1]
	ds_read_b128 v[40:43], v30 offset:9216
	s_waitcnt lgkmcnt(3)
	v_pk_fma_f32 v[138:139], v[136:137], v[54:55], v[138:139] op_sel:[1,0,0]
	v_pk_fma_f32 v[126:127], v[136:137], v[52:53], v[126:127] op_sel:[1,0,0]
	ds_read_b128 v[52:55], v30 offset:10240
	s_waitcnt lgkmcnt(3)
	v_pk_fma_f32 v[138:139], v[134:135], v[58:59], v[138:139] op_sel:[1,0,0]
	v_pk_fma_f32 v[126:127], v[134:135], v[56:57], v[126:127] op_sel:[1,0,0]
	ds_read_b128 v[56:59], v30 offset:11264
	s_waitcnt lgkmcnt(3)
	v_pk_fma_f32 v[138:139], v[132:133], v[38:39], v[138:139] op_sel_hi:[0,1,1]
	v_pk_fma_f32 v[126:127], v[132:133], v[36:37], v[126:127] op_sel_hi:[0,1,1]
	ds_read_b128 v[36:39], v30 offset:12288
	s_waitcnt lgkmcnt(3)
	v_pk_fma_f32 v[138:139], v[130:131], v[42:43], v[138:139] op_sel_hi:[0,1,1]
	v_pk_fma_f32 v[126:127], v[130:131], v[40:41], v[126:127] op_sel_hi:[0,1,1]
	ds_read_b128 v[40:43], v30 offset:13312
	s_waitcnt lgkmcnt(3)
	v_pk_fma_f32 v[138:139], v[132:133], v[54:55], v[138:139] op_sel:[1,0,0]
	v_pk_fma_f32 v[126:127], v[132:133], v[52:53], v[126:127] op_sel:[1,0,0]
	ds_read_b128 v[52:55], v30 offset:14336
	s_waitcnt lgkmcnt(3)
	v_pk_fma_f32 v[138:139], v[130:131], v[58:59], v[138:139] op_sel:[1,0,0]
	v_pk_fma_f32 v[126:127], v[130:131], v[56:57], v[126:127] op_sel:[1,0,0]
	ds_read_b128 v[56:59], v30 offset:15360
	s_waitcnt lgkmcnt(3)
	v_pk_fma_f32 v[138:139], v[128:129], v[38:39], v[138:139] op_sel_hi:[0,1,1]
	v_pk_fma_f32 v[126:127], v[128:129], v[36:37], v[126:127] op_sel_hi:[0,1,1]
	s_waitcnt lgkmcnt(2)
	v_pk_fma_f32 v[138:139], v[124:125], v[42:43], v[138:139] op_sel_hi:[0,1,1]
	v_pk_fma_f32 v[126:127], v[124:125], v[40:41], v[126:127] op_sel_hi:[0,1,1]
	s_waitcnt lgkmcnt(1)
	v_pk_fma_f32 v[138:139], v[128:129], v[54:55], v[138:139] op_sel:[1,0,0]
	v_pk_fma_f32 v[126:127], v[128:129], v[52:53], v[126:127] op_sel:[1,0,0]
	s_waitcnt lgkmcnt(0)
	v_pk_fma_f32 v[138:139], v[124:125], v[58:59], v[138:139] op_sel:[1,0,0]
	v_pk_fma_f32 v[126:127], v[124:125], v[56:57], v[126:127] op_sel:[1,0,0]
	v_mov_b32_e32 v124, v126
	v_mov_b32_e32 v125, v127
	v_mov_b32_e32 v128, v138
	v_mov_b32_e32 v129, v139
	s_nop 1
	v_add_f32_dpp v0, v124, v124 quad_perm:[1,0,3,2] row_mask:0xf bank_mask:0xf bound_ctrl:1
	s_nop 1
	v_add_f32_dpp v0, v0, v0 quad_perm:[2,3,0,1] row_mask:0xf bank_mask:0xf bound_ctrl:1
	s_nop 1
	v_add_f32_dpp v0, v0, v0 row_half_mirror row_mask:0xf bank_mask:0xf bound_ctrl:1
	s_nop 1
	v_add_f32_dpp v0, v0, v0 row_mirror row_mask:0xf bank_mask:0xf bound_ctrl:1
	s_nop 0
	v_readlane_b32 s74, v0, 0
	v_readlane_b32 s1, v0, 16
	v_readlane_b32 s75, v0, 32
	v_readlane_b32 s3, v0, 48
	v_add_f32_dpp v0, v125, v125 quad_perm:[1,0,3,2] row_mask:0xf bank_mask:0xf bound_ctrl:1
	s_nop 1
	v_add_f32_dpp v0, v0, v0 quad_perm:[2,3,0,1] row_mask:0xf bank_mask:0xf bound_ctrl:1
	s_nop 1
	v_add_f32_dpp v0, v0, v0 row_half_mirror row_mask:0xf bank_mask:0xf bound_ctrl:1
	s_nop 1
	v_add_f32_dpp v0, v0, v0 row_mirror row_mask:0xf bank_mask:0xf bound_ctrl:1
	s_nop 0
	v_readlane_b32 s72, v0, 0
	v_readlane_b32 s4, v0, 16
	v_readlane_b32 s73, v0, 32
	v_readlane_b32 s18, v0, 48
	v_add_f32_dpp v0, v128, v128 quad_perm:[1,0,3,2] row_mask:0xf bank_mask:0xf bound_ctrl:1
	s_nop 1
	v_add_f32_dpp v0, v0, v0 quad_perm:[2,3,0,1] row_mask:0xf bank_mask:0xf bound_ctrl:1
	s_nop 1
	v_add_f32_dpp v0, v0, v0 row_half_mirror row_mask:0xf bank_mask:0xf bound_ctrl:1
	s_nop 1
	v_add_f32_dpp v0, v0, v0 row_mirror row_mask:0xf bank_mask:0xf bound_ctrl:1
	s_nop 0
	v_readlane_b32 vcc_lo, v0, 0
	v_readlane_b32 s19, v0, 16
	v_readlane_b32 vcc_hi, v0, 32
	v_readlane_b32 s23, v0, 48
	v_add_f32_dpp v0, v129, v129 quad_perm:[1,0,3,2] row_mask:0xf bank_mask:0xf bound_ctrl:1
	s_nop 1
	v_add_f32_dpp v0, v0, v0 quad_perm:[2,3,0,1] row_mask:0xf bank_mask:0xf bound_ctrl:1
	s_nop 1
	v_add_f32_dpp v0, v0, v0 row_half_mirror row_mask:0xf bank_mask:0xf bound_ctrl:1
	s_nop 1
	v_add_f32_dpp v0, v0, v0 row_mirror row_mask:0xf bank_mask:0xf bound_ctrl:1
	s_nop 0
	v_readlane_b32 s48, v0, 0
	v_readlane_b32 s33, v0, 16
	v_readlane_b32 s49, v0, 32
	v_readlane_b32 s51, v0, 48
	s_and_saveexec_b64 s[16:17], s[10:11]
	s_cbranch_execz .LBB0_272
; __device__ __forceinline__ float log_sigmoid_f(float x) { return fminf(x, 0.f) - log1pf(expf(-fabsf(x))); }
; __device__ __forceinline__ void row_process(const RowArgs& R, int m, int lane, const RowRaw& q, const float (&gp)[2][8], const float (&gn)[2][8], const f32x4 bf, const LAS f32x4* afl) {
;     ...
;             acc[0] = wave_sum(acc[0]); acc[1] = wave_sum(acc[1]); acc[2] = wave_sum(acc[2]); acc[3] = wave_sum(acc[3]);
;             if (lane == 0) { f32x4 o; o[0] = log_sigmoid_f(acc[0] + bf[0]); o[1] = log_sigmoid_f(acc[1] + bf[1]); o[2] = log_sigmoid_f(acc[2] + bf[2]); o[3] = log_sigmoid_f(acc[3] + bf[3]); *(f32x4*)(R.LOGF + (size_t)m * 4) = o; }
	v_mov_b32_e32 v126, s1
	v_mov_b32_e32 v127, s3
	v_pk_add_f32 v[126:127], s[74:75], v[126:127]
	v_mov_b32_e32 v124, s33
	v_add_f32_e32 v126, v126, v127
	v_add_f32_e32 v126, v32, v126
	v_mul_f32_e64 v127, |v126|, s22
	v_fma_f32 v128, |v126|, s22, -v127
	v_rndne_f32_e32 v129, v127
	v_fma_f32 v128, |v126|, s29, v128
	v_sub_f32_e32 v127, v127, v129
	v_add_f32_e32 v127, v127, v128
	v_exp_f32_e32 v127, v127
	v_cvt_i32_f32_e32 v128, v129
	v_mov_b32_e32 v125, s51
	v_pk_add_f32 v[124:125], s[48:49], v[124:125]
	s_mov_b32 s1, 0xc2b17218
	v_add_f32_e32 v0, v124, v125
	v_mov_b32_e32 v124, s19
	v_mov_b32_e32 v125, s23
	v_pk_add_f32 v[124:125], vcc, v[124:125]
	v_ldexp_f32 v127, v127, v128
	v_cmp_ngt_f32_e64 vcc, |v126|, s55
	v_add_f32_e32 v143, v124, v125
	v_mov_b32_e32 v124, s4
	v_cndmask_b32_e32 v127, 0, v127, vcc
	v_cmp_nlt_f32_e64 vcc, |v126|, s1
	v_mov_b32_e32 v125, s18
	v_pk_add_f32 v[124:125], s[72:73], v[124:125]
	v_cndmask_b32_e32 v164, v235, v127, vcc
	v_add_f32_e32 v128, 1.0, v164
	v_add_f32_e32 v125, v124, v125
	v_min_f32_e32 v124, 0, v126
	v_add_f32_e32 v126, -1.0, v128
	v_sub_f32_e32 v127, v126, v128
	v_add_f32_e32 v131, v33, v125
	v_add_f32_e32 v127, 1.0, v127
	v_sub_f32_e32 v126, v164, v126
	v_mul_f32_e64 v125, |v131|, s22
	v_add_f32_e32 v129, v126, v127
	v_fma_f32 v126, |v131|, s22, -v125
	v_rndne_f32_e32 v127, v125
	v_fma_f32 v126, |v131|, s29, v126
	v_sub_f32_e32 v125, v125, v127
	v_add_f32_e32 v125, v125, v126
	v_exp_f32_e32 v132, v125
	v_cvt_i32_f32_e32 v133, v127
	v_cvt_f64_f32_e32 v[126:127], v128
	v_frexp_exp_i32_f64_e32 v134, v[126:127]
	v_cmp_ngt_f32_e64 vcc, |v131|, s55
	v_ldexp_f32 v126, v132, v133
	v_min_f32_e32 v125, 0, v131
	v_cndmask_b32_e32 v126, 0, v126, vcc
	v_cmp_nlt_f32_e64 vcc, |v131|, s1
	s_mov_b32 s4, 0x3f2aaaab
	v_frexp_mant_f32_e32 v130, v128
	v_cndmask_b32_e32 v165, v235, v126, vcc
	v_add_f32_e32 v131, 1.0, v165
	v_add_f32_e32 v126, -1.0, v131
	v_sub_f32_e32 v127, v126, v131
	v_add_f32_e32 v127, 1.0, v127
	v_sub_f32_e32 v126, v165, v126
	v_add_f32_e32 v132, v126, v127
	v_frexp_mant_f32_e32 v133, v131
	v_cvt_f64_f32_e32 v[126:127], v131
	v_frexp_exp_i32_f64_e32 v126, v[126:127]
	v_cmp_gt_f32_e32 vcc, s4, v133
	s_mov_b32 s18, 0x3ecc95a3
	s_mov_b32 s48, 0x3e9b6dac
	v_subbrev_co_u32_e32 v154, vcc, 0, v126, vcc
	v_cmp_gt_f32_e32 vcc, s4, v130
	s_mov_b32 s72, 0x3f2aaada
	s_mov_b32 s74, 0x3f317218
	v_subbrev_co_u32_e32 v155, vcc, 0, v134, vcc
	v_sub_u32_e32 v127, 0, v155
	v_ldexp_f32 v126, v128, v127
	v_ldexp_f32 v128, v129, v127
	v_sub_u32_e32 v129, 0, v154
	v_ldexp_f32 v127, v131, v129
	v_pk_add_f32 v[130:131], v[126:127], 1.0 op_sel_hi:[1,0]
	v_ldexp_f32 v129, v132, v129
	v_pk_add_f32 v[132:133], v[130:131], -1.0 op_sel_hi:[1,0]
	v_pk_add_f32 v[138:139], v[126:127], -1.0 op_sel_hi:[1,0]
	v_pk_add_f32 v[132:133], v[126:127], v[132:133] neg_lo:[0,1] neg_hi:[0,1]
	v_pk_add_f32 v[148:149], v[138:139], 1.0 op_sel_hi:[1,0]
	v_pk_add_f32 v[132:133], v[128:129], v[132:133]
	v_pk_add_f32 v[126:127], v[126:127], v[148:149] neg_lo:[0,1] neg_hi:[0,1]
	v_pk_add_f32 v[134:135], v[130:131], v[132:133]
	v_pk_add_f32 v[126:127], v[128:129], v[126:127]
	v_rcp_f32_e32 v136, v134
	v_rcp_f32_e32 v137, v135
	v_pk_add_f32 v[128:129], v[138:139], v[126:127]
	v_pk_add_f32 v[130:131], v[130:131], v[134:135] neg_lo:[0,1] neg_hi:[0,1]
	v_pk_add_f32 v[138:139], v[138:139], v[128:129] neg_lo:[0,1] neg_hi:[0,1]
	v_pk_add_f32 v[130:131], v[132:133], v[130:131]
	v_pk_mul_f32 v[132:133], v[128:129], v[136:137]
	v_pk_add_f32 v[126:127], v[126:127], v[138:139]
	v_pk_mul_f32 v[138:139], v[134:135], v[132:133]
	s_mov_b32 s82, 0xb102e308
	v_pk_fma_f32 v[148:149], v[132:133], v[134:135], v[138:139] neg_lo:[0,0,1] neg_hi:[0,0,1]
	s_mov_b32 s3, 0x7f800000
	v_pk_fma_f32 v[148:149], v[132:133], v[130:131], v[148:149]
	v_cmp_neq_f32_e32 vcc, s3, v164
	v_pk_add_f32 v[150:151], v[138:139], v[148:149]
	v_add_f32_e32 v0, v35, v0
	v_pk_add_f32 v[152:153], v[128:129], v[150:151] neg_lo:[0,1] neg_hi:[0,1]
	v_pk_add_f32 v[138:139], v[150:151], v[138:139] neg_lo:[0,1] neg_hi:[0,1]
	v_pk_add_f32 v[128:129], v[128:129], v[152:153] neg_lo:[0,1] neg_hi:[0,1]
	s_nop 0
	v_pk_add_f32 v[128:129], v[128:129], v[150:151] neg_lo:[0,1] neg_hi:[0,1]
	s_nop 0
	v_pk_add_f32 v[126:127], v[126:127], v[128:129]
	v_pk_add_f32 v[128:129], v[138:139], v[148:149] neg_lo:[0,1] neg_hi:[0,1]
	s_nop 0
	v_pk_add_f32 v[126:127], v[128:129], v[126:127]
	s_nop 0
	v_pk_add_f32 v[128:129], v[152:153], v[126:127]
	s_nop 0
	v_pk_mul_f32 v[138:139], v[136:137], v[128:129]
	s_nop 0
	v_pk_mul_f32 v[148:149], v[134:135], v[138:139]
	s_nop 0
	v_pk_fma_f32 v[134:135], v[138:139], v[134:135], v[148:149] neg_lo:[0,0,1] neg_hi:[0,0,1]
	s_nop 0
	v_pk_fma_f32 v[130:131], v[138:139], v[130:131], v[134:135]
	v_pk_add_f32 v[134:135], v[152:153], v[128:129] neg_lo:[0,1] neg_hi:[0,1]
	s_nop 0
	v_pk_add_f32 v[126:127], v[126:127], v[134:135]
	v_pk_add_f32 v[134:135], v[148:149], v[130:131]
	s_nop 0
	v_pk_add_f32 v[150:151], v[128:129], v[134:135] neg_lo:[0,1] neg_hi:[0,1]
	v_pk_add_f32 v[148:149], v[134:135], v[148:149] neg_lo:[0,1] neg_hi:[0,1]
	v_pk_add_f32 v[128:129], v[128:129], v[150:151] neg_lo:[0,1] neg_hi:[0,1]
	s_nop 0
	v_pk_add_f32 v[128:129], v[128:129], v[134:135] neg_lo:[0,1] neg_hi:[0,1]
	v_cvt_f32_i32_e32 v135, v154
	v_pk_add_f32 v[126:127], v[126:127], v[128:129]
	v_pk_add_f32 v[128:129], v[148:149], v[130:131] neg_lo:[0,1] neg_hi:[0,1]
	v_cvt_f32_i32_e32 v134, v155
	v_pk_add_f32 v[126:127], v[128:129], v[126:127]
	v_pk_add_f32 v[128:129], v[132:133], v[138:139]
	v_pk_add_f32 v[126:127], v[150:151], v[126:127]
	v_pk_add_f32 v[130:131], v[128:129], v[132:133] neg_lo:[0,1] neg_hi:[0,1]
; __device__ __forceinline__ float log_sigmoid_f(float x) { return fminf(x, 0.f) - log1pf(expf(-fabsf(x))); }
; __device__ __forceinline__ void row_process(const RowArgs& R, int m, int lane, const RowRaw& q, const float (&gp)[2][8], const float (&gn)[2][8], const f32x4 bf, const LAS f32x4* afl) {
;     ...
;             acc[0] = wave_sum(acc[0]); acc[1] = wave_sum(acc[1]); acc[2] = wave_sum(acc[2]); acc[3] = wave_sum(acc[3]);
;             if (lane == 0) { f32x4 o; o[0] = log_sigmoid_f(acc[0] + bf[0]); o[1] = log_sigmoid_f(acc[1] + bf[1]); o[2] = log_sigmoid_f(acc[2] + bf[2]); o[3] = log_sigmoid_f(acc[3] + bf[3]); *(f32x4*)(R.LOGF + (size_t)m * 4) = o; }
	v_pk_mul_f32 v[126:127], v[136:137], v[126:127]
	v_pk_add_f32 v[130:131], v[138:139], v[130:131] neg_lo:[0,1] neg_hi:[0,1]
	v_mov_b64_e32 v[136:137], s[18:19]
	v_pk_add_f32 v[126:127], v[130:131], v[126:127]
	v_pk_mul_f32 v[148:149], v[134:135], s[74:75] op_sel_hi:[1,0]
	v_pk_add_f32 v[130:131], v[128:129], v[126:127]
	v_pk_fma_f32 v[150:151], v[134:135], s[74:75], v[148:149] op_sel_hi:[1,0,1] neg_lo:[0,0,1] neg_hi:[0,0,1]
	v_pk_mul_f32 v[132:133], v[130:131], v[130:131]
	v_pk_add_f32 v[128:129], v[130:131], v[128:129] neg_lo:[0,1] neg_hi:[0,1]
	v_pk_fma_f32 v[138:139], v[132:133], s[48:49], v[136:137] op_sel_hi:[1,0,0]
	v_pk_add_f32 v[126:127], v[126:127], v[128:129] neg_lo:[0,1] neg_hi:[0,1]
	v_ldexp_f32 v128, v130, 1
	v_pk_fma_f32 v[138:139], v[132:133], v[138:139], s[72:73] op_sel_hi:[1,1,0]
	v_ldexp_f32 v129, v131, 1
	v_pk_mul_f32 v[130:131], v[130:131], v[132:133]
	v_mov_b32_e32 v153, v129
	v_pk_mul_f32 v[130:131], v[130:131], v[138:139]
	v_ldexp_f32 v126, v126, 1
	v_pk_add_f32 v[132:133], v[128:129], v[130:131]
	v_pk_fma_f32 v[134:135], v[134:135], s[82:83], v[150:151] op_sel_hi:[1,0,1]
	v_pk_add_f32 v[128:129], v[132:133], v[128:129] neg_lo:[0,1] neg_hi:[0,1]
	v_ldexp_f32 v127, v127, 1
	v_pk_add_f32 v[128:129], v[130:131], v[128:129] neg_lo:[0,1] neg_hi:[0,1]
	v_mov_b32_e32 v138, v148
	v_mov_b32_e32 v139, v131
	v_mov_b32_e32 v152, v134
	v_pk_add_f32 v[130:131], v[126:127], v[128:129]
	v_mov_b32_e32 v128, v148
	v_mov_b32_e32 v126, v134
	v_pk_add_f32 v[138:139], v[138:139], v[152:153]
	v_pk_add_f32 v[152:153], v[128:129], v[126:127]
	v_mov_b32_e32 v126, v132
	v_mov_b32_e32 v128, v130
	v_pk_add_f32 v[150:151], v[148:149], v[134:135]
	v_pk_add_f32 v[126:127], v[126:127], v[128:129]
	v_pk_add_f32 v[128:129], v[132:133], v[130:131]
	v_mov_b32_e32 v154, v150
	v_mov_b32_e32 v155, v149
	v_mov_b32_e32 v156, v128
	v_mov_b32_e32 v157, v135
	v_pk_add_f32 v[126:127], v[138:139], v[126:127]
	v_pk_add_f32 v[138:139], v[150:151], v[128:129]
	v_pk_add_f32 v[158:159], v[154:155], v[156:157]
	v_mov_b32_e32 v160, v128
	v_mov_b32_e32 v161, v139
	v_mov_b32_e32 v162, v132
	v_mov_b32_e32 v163, v151
	v_pk_add_f32 v[154:155], v[158:159], v[154:155] neg_lo:[0,1] neg_hi:[0,1]
	v_pk_add_f32 v[160:161], v[160:161], v[162:163] neg_lo:[0,1] neg_hi:[0,1]
	v_pk_add_f32 v[158:159], v[150:151], v[148:149] neg_lo:[0,1] neg_hi:[0,1]
	v_pk_add_f32 v[156:157], v[156:157], v[154:155] neg_lo:[0,1] neg_hi:[0,1]
	v_mov_b32_e32 v162, v150
	v_mov_b32_e32 v163, v139
	v_mov_b32_e32 v149, v161
	v_mov_b32_e32 v155, v133
	v_pk_add_f32 v[132:133], v[128:129], v[132:133] neg_lo:[0,1] neg_hi:[0,1]
	v_pk_add_f32 v[148:149], v[162:163], v[148:149] neg_lo:[0,1] neg_hi:[0,1]
	v_pk_add_f32 v[158:159], v[134:135], v[158:159] neg_lo:[0,1] neg_hi:[0,1]
	v_pk_add_f32 v[126:127], v[126:127], v[154:155] neg_lo:[0,1] neg_hi:[0,1]
	v_pk_add_f32 v[132:133], v[130:131], v[132:133] neg_lo:[0,1] neg_hi:[0,1]
	v_mov_b32_e32 v135, v151
	v_mov_b32_e32 v131, v129
	v_pk_add_f32 v[126:127], v[152:153], v[126:127] neg_lo:[0,1] neg_hi:[0,1]
	v_pk_add_f32 v[134:135], v[134:135], v[148:149] neg_lo:[0,1] neg_hi:[0,1]
	v_pk_add_f32 v[128:129], v[130:131], v[160:161] neg_lo:[0,1] neg_hi:[0,1]
	v_pk_add_f32 v[148:149], v[156:157], v[126:127]
	v_pk_add_f32 v[130:131], v[128:129], v[134:135]
	v_mov_b32_e32 v129, v127
	v_pk_add_f32 v[126:127], v[158:159], v[128:129]
	v_mov_b32_e32 v135, v157
	v_pk_add_f32 v[126:127], v[126:127], v[134:135] neg_lo:[0,1] neg_hi:[0,1]
	v_mov_b32_e32 v128, v130
	v_mov_b32_e32 v129, v149
	v_pk_add_f32 v[128:129], v[128:129], v[126:127] neg_lo:[0,1] neg_hi:[0,1]
	v_pk_add_f32 v[126:127], v[132:133], v[126:127] neg_lo:[0,1] neg_hi:[0,1]
	v_pk_add_f32 v[128:129], v[134:135], v[128:129] neg_lo:[0,1] neg_hi:[0,1]
	s_mov_b32 s18, 0x33800000
	v_pk_add_f32 v[126:127], v[126:127], v[128:129]
	v_pk_add_f32 v[128:129], v[148:149], v[130:131]
	s_nop 0
	v_pk_add_f32 v[130:131], v[138:139], v[128:129]
	s_nop 0
	v_pk_add_f32 v[132:133], v[130:131], v[138:139] neg_lo:[0,1] neg_hi:[0,1]
	s_nop 0
	v_pk_add_f32 v[128:129], v[128:129], v[132:133] neg_lo:[0,1] neg_hi:[0,1]
	s_nop 0
	v_pk_add_f32 v[126:127], v[126:127], v[128:129]
	v_add_f32_e32 v128, v34, v143
	v_mul_f32_e64 v129, |v128|, s22
	v_pk_add_f32 v[126:127], v[130:131], v[126:127]
	v_fma_f32 v130, |v128|, s22, -v129
	v_rndne_f32_e32 v131, v129
	v_fma_f32 v130, |v128|, s29, v130
	v_sub_f32_e32 v129, v129, v131
	v_add_f32_e32 v129, v129, v130
	v_cndmask_b32_e32 v126, v235, v126, vcc
	v_cmp_neq_f32_e32 vcc, s3, v165
	v_exp_f32_e32 v129, v129
	v_cvt_i32_f32_e32 v130, v131
	v_cndmask_b32_e32 v127, v235, v127, vcc
	v_cmp_lt_f32_e64 vcc, |v165|, s18
	s_nop 1
	v_cndmask_b32_e32 v127, v127, v165, vcc
	v_cmp_lt_f32_e64 vcc, |v164|, s18
	s_nop 1
	v_cndmask_b32_e32 v126, v126, v164, vcc
	v_pk_add_f32 v[124:125], v[124:125], v[126:127] neg_lo:[0,1] neg_hi:[0,1]
	v_ldexp_f32 v127, v129, v130
	v_cmp_ngt_f32_e64 vcc, |v128|, s55
	v_min_f32_e32 v126, 0, v128
	s_nop 0
	v_cndmask_b32_e32 v127, 0, v127, vcc
	v_cmp_nlt_f32_e64 vcc, |v128|, s1
	s_nop 1
	v_cndmask_b32_e32 v143, v235, v127, vcc
	v_add_f32_e32 v130, 1.0, v143
	v_add_f32_e32 v127, -1.0, v130
	v_sub_f32_e32 v128, v127, v130
	v_add_f32_e32 v128, 1.0, v128
	v_sub_f32_e32 v127, v143, v127
	v_add_f32_e32 v131, v127, v128
	v_mul_f32_e64 v127, |v0|, s22
	v_fma_f32 v128, |v0|, s22, -v127
	v_rndne_f32_e32 v129, v127
	v_fma_f32 v128, |v0|, s29, v128
	v_sub_f32_e32 v127, v127, v129
	v_add_f32_e32 v127, v127, v128
	v_exp_f32_e32 v133, v127
	v_cvt_i32_f32_e32 v134, v129
	v_cvt_f64_f32_e32 v[128:129], v130
	v_frexp_exp_i32_f64_e32 v135, v[128:129]
	v_cmp_ngt_f32_e64 vcc, |v0|, s55
	v_ldexp_f32 v128, v133, v134
; __device__ __forceinline__ float log_sigmoid_f(float x) { return fminf(x, 0.f) - log1pf(expf(-fabsf(x))); }
; __device__ __forceinline__ void row_process(const RowArgs& R, int m, int lane, const RowRaw& q, const float (&gp)[2][8], const float (&gn)[2][8], const f32x4 bf, const LAS f32x4* afl) {
;     ...
;             acc[0] = wave_sum(acc[0]); acc[1] = wave_sum(acc[1]); acc[2] = wave_sum(acc[2]); acc[3] = wave_sum(acc[3]);
;             if (lane == 0) { f32x4 o; o[0] = log_sigmoid_f(acc[0] + bf[0]); o[1] = log_sigmoid_f(acc[1] + bf[1]); o[2] = log_sigmoid_f(acc[2] + bf[2]); o[3] = log_sigmoid_f(acc[3] + bf[3]); *(f32x4*)(R.LOGF + (size_t)m * 4) = o; }
	v_min_f32_e32 v127, 0, v0
	v_cndmask_b32_e32 v128, 0, v128, vcc
	v_cmp_nlt_f32_e64 vcc, |v0|, s1
	v_frexp_mant_f32_e32 v132, v130
	s_nop 0
	v_cndmask_b32_e32 v0, v235, v128, vcc
	v_add_f32_e32 v133, 1.0, v0
	v_add_f32_e32 v128, -1.0, v133
	v_sub_f32_e32 v129, v128, v133
	v_add_f32_e32 v129, 1.0, v129
	v_sub_f32_e32 v128, v0, v128
	v_add_f32_e32 v134, v128, v129
	v_frexp_mant_f32_e32 v138, v133
	v_cvt_f64_f32_e32 v[128:129], v133
	v_frexp_exp_i32_f64_e32 v128, v[128:129]
	v_cmp_gt_f32_e32 vcc, s4, v138
	s_nop 1
	v_subbrev_co_u32_e32 v158, vcc, 0, v128, vcc
	v_cmp_gt_f32_e32 vcc, s4, v132
	s_nop 1
	v_subbrev_co_u32_e32 v159, vcc, 0, v135, vcc
	v_sub_u32_e32 v129, 0, v159
	v_ldexp_f32 v128, v130, v129
	v_ldexp_f32 v130, v131, v129
	v_sub_u32_e32 v131, 0, v158
	v_ldexp_f32 v129, v133, v131
	v_pk_add_f32 v[132:133], v[128:129], 1.0 op_sel_hi:[1,0]
	v_ldexp_f32 v131, v134, v131
	v_pk_add_f32 v[134:135], v[132:133], -1.0 op_sel_hi:[1,0]
	v_pk_add_f32 v[150:151], v[128:129], -1.0 op_sel_hi:[1,0]
	v_pk_add_f32 v[134:135], v[128:129], v[134:135] neg_lo:[0,1] neg_hi:[0,1]
	v_pk_add_f32 v[152:153], v[150:151], 1.0 op_sel_hi:[1,0]
	v_pk_add_f32 v[134:135], v[130:131], v[134:135]
	v_pk_add_f32 v[128:129], v[128:129], v[152:153] neg_lo:[0,1] neg_hi:[0,1]
	v_pk_add_f32 v[138:139], v[132:133], v[134:135]
	v_pk_add_f32 v[128:129], v[130:131], v[128:129]
	v_rcp_f32_e32 v148, v138
	v_rcp_f32_e32 v149, v139
	v_pk_add_f32 v[130:131], v[150:151], v[128:129]
	v_pk_add_f32 v[132:133], v[132:133], v[138:139] neg_lo:[0,1] neg_hi:[0,1]
	v_pk_add_f32 v[150:151], v[150:151], v[130:131] neg_lo:[0,1] neg_hi:[0,1]
	v_pk_add_f32 v[132:133], v[134:135], v[132:133]
	v_pk_mul_f32 v[134:135], v[130:131], v[148:149]
	v_pk_add_f32 v[128:129], v[128:129], v[150:151]
	v_pk_mul_f32 v[150:151], v[138:139], v[134:135]
	v_cmp_neq_f32_e32 vcc, s3, v143
	v_pk_fma_f32 v[152:153], v[134:135], v[138:139], v[150:151] neg_lo:[0,0,1] neg_hi:[0,0,1]
	s_nop 0
	v_pk_fma_f32 v[152:153], v[134:135], v[132:133], v[152:153]
	s_nop 0
	v_pk_add_f32 v[154:155], v[150:151], v[152:153]
	s_nop 0
	v_pk_add_f32 v[156:157], v[130:131], v[154:155] neg_lo:[0,1] neg_hi:[0,1]
	v_pk_add_f32 v[150:151], v[154:155], v[150:151] neg_lo:[0,1] neg_hi:[0,1]
	v_pk_add_f32 v[130:131], v[130:131], v[156:157] neg_lo:[0,1] neg_hi:[0,1]
	s_nop 0
	v_pk_add_f32 v[130:131], v[130:131], v[154:155] neg_lo:[0,1] neg_hi:[0,1]
	s_nop 0
	v_pk_add_f32 v[128:129], v[128:129], v[130:131]
	v_pk_add_f32 v[130:131], v[150:151], v[152:153] neg_lo:[0,1] neg_hi:[0,1]
	s_nop 0
	v_pk_add_f32 v[128:129], v[130:131], v[128:129]
	s_nop 0
	v_pk_add_f32 v[130:131], v[156:157], v[128:129]
	s_nop 0
	v_pk_mul_f32 v[150:151], v[148:149], v[130:131]
	s_nop 0
	v_pk_mul_f32 v[152:153], v[138:139], v[150:151]
	s_nop 0
	v_pk_fma_f32 v[138:139], v[150:151], v[138:139], v[152:153] neg_lo:[0,0,1] neg_hi:[0,0,1]
	s_nop 0
	v_pk_fma_f32 v[132:133], v[150:151], v[132:133], v[138:139]
	v_pk_add_f32 v[138:139], v[156:157], v[130:131] neg_lo:[0,1] neg_hi:[0,1]
	s_nop 0
	v_pk_add_f32 v[128:129], v[128:129], v[138:139]
	v_pk_add_f32 v[138:139], v[152:153], v[132:133]
	s_nop 0
	v_pk_add_f32 v[154:155], v[130:131], v[138:139] neg_lo:[0,1] neg_hi:[0,1]
	v_pk_add_f32 v[152:153], v[138:139], v[152:153] neg_lo:[0,1] neg_hi:[0,1]
	v_pk_add_f32 v[130:131], v[130:131], v[154:155] neg_lo:[0,1] neg_hi:[0,1]
	s_nop 0
	v_pk_add_f32 v[130:131], v[130:131], v[138:139] neg_lo:[0,1] neg_hi:[0,1]
	s_nop 0
	v_pk_add_f32 v[128:129], v[128:129], v[130:131]
	v_pk_add_f32 v[130:131], v[152:153], v[132:133] neg_lo:[0,1] neg_hi:[0,1]
	s_nop 0
	v_pk_add_f32 v[128:129], v[130:131], v[128:129]
	v_pk_add_f32 v[130:131], v[134:135], v[150:151]
	v_pk_add_f32 v[128:129], v[154:155], v[128:129]
	v_pk_add_f32 v[132:133], v[130:131], v[134:135] neg_lo:[0,1] neg_hi:[0,1]
	v_pk_mul_f32 v[128:129], v[148:149], v[128:129]
	v_pk_add_f32 v[132:133], v[150:151], v[132:133] neg_lo:[0,1] neg_hi:[0,1]
	v_cvt_f32_i32_e32 v135, v158
	v_pk_add_f32 v[128:129], v[132:133], v[128:129]
	v_cvt_f32_i32_e32 v134, v159
	v_pk_add_f32 v[132:133], v[130:131], v[128:129]
	v_pk_mul_f32 v[148:149], v[134:135], s[74:75] op_sel_hi:[1,0]
	v_pk_mul_f32 v[138:139], v[132:133], v[132:133]
	v_pk_add_f32 v[130:131], v[132:133], v[130:131] neg_lo:[0,1] neg_hi:[0,1]
; __device__ __forceinline__ float log_sigmoid_f(float x) { return fminf(x, 0.f) - log1pf(expf(-fabsf(x))); }
; __device__ __forceinline__ void row_process(const RowArgs& R, int m, int lane, const RowRaw& q, const float (&gp)[2][8], const float (&gn)[2][8], const f32x4 bf, const LAS f32x4* afl) {
;     ...
;             acc[0] = wave_sum(acc[0]); acc[1] = wave_sum(acc[1]); acc[2] = wave_sum(acc[2]); acc[3] = wave_sum(acc[3]);
;             if (lane == 0) { f32x4 o; o[0] = log_sigmoid_f(acc[0] + bf[0]); o[1] = log_sigmoid_f(acc[1] + bf[1]); o[2] = log_sigmoid_f(acc[2] + bf[2]); o[3] = log_sigmoid_f(acc[3] + bf[3]); *(f32x4*)(R.LOGF + (size_t)m * 4) = o; }
	v_pk_fma_f32 v[136:137], v[138:139], s[48:49], v[136:137] op_sel_hi:[1,0,0]
	v_pk_add_f32 v[128:129], v[128:129], v[130:131] neg_lo:[0,1] neg_hi:[0,1]
	v_ldexp_f32 v130, v132, 1
	v_pk_fma_f32 v[136:137], v[138:139], v[136:137], s[72:73] op_sel_hi:[1,1,0]
	v_ldexp_f32 v131, v133, 1
	v_pk_mul_f32 v[132:133], v[132:133], v[138:139]
	v_pk_fma_f32 v[150:151], v[134:135], s[74:75], v[148:149] op_sel_hi:[1,0,1] neg_lo:[0,0,1] neg_hi:[0,0,1]
	v_pk_mul_f32 v[132:133], v[132:133], v[136:137]
	v_mov_b32_e32 v153, v131
	v_pk_add_f32 v[136:137], v[130:131], v[132:133]
	v_ldexp_f32 v128, v128, 1
	v_pk_add_f32 v[130:131], v[136:137], v[130:131] neg_lo:[0,1] neg_hi:[0,1]
	v_pk_fma_f32 v[134:135], v[134:135], s[82:83], v[150:151] op_sel_hi:[1,0,1]
	v_ldexp_f32 v129, v129, 1
	v_pk_add_f32 v[130:131], v[132:133], v[130:131] neg_lo:[0,1] neg_hi:[0,1]
	v_mov_b32_e32 v138, v148
	v_mov_b32_e32 v139, v133
	v_mov_b32_e32 v152, v134
	v_pk_add_f32 v[132:133], v[128:129], v[130:131]
	v_mov_b32_e32 v130, v148
	v_mov_b32_e32 v128, v134
	v_pk_add_f32 v[138:139], v[138:139], v[152:153]
	v_pk_add_f32 v[152:153], v[130:131], v[128:129]
	v_mov_b32_e32 v128, v136
	v_mov_b32_e32 v130, v132
	v_pk_add_f32 v[150:151], v[148:149], v[134:135]
	v_pk_add_f32 v[128:129], v[128:129], v[130:131]
	v_pk_add_f32 v[130:131], v[136:137], v[132:133]
	v_mov_b32_e32 v154, v150
	v_mov_b32_e32 v155, v149
	v_mov_b32_e32 v156, v130
	v_mov_b32_e32 v157, v135
	v_pk_add_f32 v[128:129], v[138:139], v[128:129]
	v_pk_add_f32 v[138:139], v[150:151], v[130:131]
	v_pk_add_f32 v[158:159], v[154:155], v[156:157]
	v_mov_b32_e32 v160, v130
	v_mov_b32_e32 v161, v139
	v_mov_b32_e32 v162, v136
	v_mov_b32_e32 v163, v151
	v_pk_add_f32 v[154:155], v[158:159], v[154:155] neg_lo:[0,1] neg_hi:[0,1]
	v_pk_add_f32 v[160:161], v[160:161], v[162:163] neg_lo:[0,1] neg_hi:[0,1]
	v_pk_add_f32 v[158:159], v[150:151], v[148:149] neg_lo:[0,1] neg_hi:[0,1]
	v_pk_add_f32 v[156:157], v[156:157], v[154:155] neg_lo:[0,1] neg_hi:[0,1]
	v_mov_b32_e32 v162, v150
	v_mov_b32_e32 v163, v139
	v_mov_b32_e32 v149, v161
	v_mov_b32_e32 v155, v137
	v_pk_add_f32 v[136:137], v[130:131], v[136:137] neg_lo:[0,1] neg_hi:[0,1]
	v_pk_add_f32 v[148:149], v[162:163], v[148:149] neg_lo:[0,1] neg_hi:[0,1]
	v_pk_add_f32 v[158:159], v[134:135], v[158:159] neg_lo:[0,1] neg_hi:[0,1]
	v_pk_add_f32 v[128:129], v[128:129], v[154:155] neg_lo:[0,1] neg_hi:[0,1]
	v_pk_add_f32 v[136:137], v[132:133], v[136:137] neg_lo:[0,1] neg_hi:[0,1]
	v_mov_b32_e32 v135, v151
	v_mov_b32_e32 v133, v131
	v_pk_add_f32 v[128:129], v[152:153], v[128:129] neg_lo:[0,1] neg_hi:[0,1]
	v_pk_add_f32 v[134:135], v[134:135], v[148:149] neg_lo:[0,1] neg_hi:[0,1]
	v_pk_add_f32 v[130:131], v[132:133], v[160:161] neg_lo:[0,1] neg_hi:[0,1]
	v_pk_add_f32 v[148:149], v[156:157], v[128:129]
	v_pk_add_f32 v[132:133], v[130:131], v[134:135]
	v_mov_b32_e32 v131, v129
	v_pk_add_f32 v[128:129], v[158:159], v[130:131]
	v_mov_b32_e32 v135, v157
	v_pk_add_f32 v[128:129], v[128:129], v[134:135] neg_lo:[0,1] neg_hi:[0,1]
	v_mov_b32_e32 v130, v132
	v_mov_b32_e32 v131, v149
	v_pk_add_f32 v[130:131], v[130:131], v[128:129] neg_lo:[0,1] neg_hi:[0,1]
	v_pk_add_f32 v[128:129], v[136:137], v[128:129] neg_lo:[0,1] neg_hi:[0,1]
	v_pk_add_f32 v[130:131], v[134:135], v[130:131] neg_lo:[0,1] neg_hi:[0,1]
	s_nop 0
	v_pk_add_f32 v[128:129], v[128:129], v[130:131]
	v_pk_add_f32 v[130:131], v[148:149], v[132:133]
	s_nop 0
	v_pk_add_f32 v[132:133], v[138:139], v[130:131]
	s_nop 0
	v_pk_add_f32 v[134:135], v[132:133], v[138:139] neg_lo:[0,1] neg_hi:[0,1]
	s_nop 0
	v_pk_add_f32 v[130:131], v[130:131], v[134:135] neg_lo:[0,1] neg_hi:[0,1]
	s_nop 0
	v_pk_add_f32 v[128:129], v[128:129], v[130:131]
	s_nop 0
	v_pk_add_f32 v[128:129], v[132:133], v[128:129]
	s_nop 0
	v_cndmask_b32_e32 v128, v235, v128, vcc
	v_cmp_neq_f32_e32 vcc, s3, v0
	s_nop 1
	v_cndmask_b32_e32 v129, v235, v129, vcc
	v_cmp_lt_f32_e64 vcc, |v0|, s18
	s_nop 1
	v_cndmask_b32_e32 v129, v129, v0, vcc
	v_cmp_lt_f32_e64 vcc, |v143|, s18
	s_lshl_b64 s[18:19], s[68:69], 4
	s_add_u32 s18, s44, s18
	v_cndmask_b32_e32 v128, v128, v143, vcc
	v_pk_add_f32 v[126:127], v[126:127], v[128:129] neg_lo:[0,1] neg_hi:[0,1]
	s_addc_u32 s19, s45, s19
	global_store_dwordx4 v1, v[124:127], s[18:19]

; __device__ __forceinline__ unsigned pk2(float lo, float hi) { return f2bf(lo) | (f2bf(hi) << 16); }
; __device__ __forceinline__ void row_process(const RowArgs& R, int m, int lane, const RowRaw& q, const float (&gp)[2][8], const float (&gn)[2][8], const f32x4 bf, const LAS f32x4* afl) {
;     ...
;     if (R.gnext) {
;         float ss = 0.f;
; #pragma unroll
;         for (int j = 0; j < 2; ++j)
; #pragma unroll
;             for (int c = 0; c < 8; ++c) ss += v[j][c] * v[j][c];
;         const float r2 = 1.0f / sqrtf(wave_sum(ss) * (1.0f / DM) + EPS);
;         float un[2][8];
; #pragma unroll
;         for (int j = 0; j < 2; ++j) {
; #pragma unroll
;             for (int c = 0; c < 8; ++c) un[j][c] = (v[j][c] * r2) * gn[j][c];
;             u32x4 w; w.x = pk2(un[j][0], un[j][1]); w.y = pk2(un[j][2], un[j][3]); w.z = pk2(un[j][4], un[j][5]); w.w = pk2(un[j][6], un[j][7]);
;             *(u32x4*)(R.U + off + 512 * j) = w;
;         }
.LBB0_294:
	s_and_b64 vcc, exec, s[6:7]
	s_cbranch_vccnz .LBB0_299
	v_pk_mul_f32 v[150:151], v[132:133], v[132:133]
	v_pk_mul_f32 v[152:153], v[136:137], v[136:137]
	v_pk_mul_f32 v[154:155], v[134:135], v[134:135]
	v_add_f32_e32 v0, v150, v152
	v_add_f32_e32 v0, v0, v151
	v_add_f32_e32 v0, v0, v153
	v_pk_mul_f32 v[156:157], v[138:139], v[138:139]
	v_add_f32_e32 v0, v0, v154
	v_add_f32_e32 v0, v0, v156
	v_add_f32_e32 v0, v0, v155
	v_pk_mul_f32 v[158:159], v[128:129], v[128:129]
	v_add_f32_e32 v0, v0, v157
	v_add_f32_e32 v0, v0, v158
	v_pk_mul_f32 v[160:161], v[130:131], v[130:131]
	v_add_f32_e32 v0, v0, v159
	v_add_f32_e32 v0, v0, v160
	v_pk_mul_f32 v[162:163], v[124:125], v[124:125]
	v_add_f32_e32 v0, v0, v161
	v_add_f32_e32 v0, v0, v162
	v_pk_mul_f32 v[164:165], v[126:127], v[126:127]
	v_add_f32_e32 v0, v0, v163
	v_add_f32_e32 v0, v0, v164
	v_add_f32_e32 v0, v0, v165
	s_nop 1
	v_add_f32_dpp v0, v0, v0 quad_perm:[1,0,3,2] row_mask:0xf bank_mask:0xf bound_ctrl:1
	s_nop 1
	v_add_f32_dpp v0, v0, v0 quad_perm:[2,3,0,1] row_mask:0xf bank_mask:0xf bound_ctrl:1
	s_nop 1
	v_add_f32_dpp v0, v0, v0 row_half_mirror row_mask:0xf bank_mask:0xf bound_ctrl:1
	s_nop 1
	v_add_f32_dpp v0, v0, v0 row_mirror row_mask:0xf bank_mask:0xf bound_ctrl:1
	s_nop 0
	v_readlane_b32 s1, v0, 16
	v_readlane_b32 s3, v0, 48
	v_readlane_b32 s12, v0, 0
	v_readlane_b32 s13, v0, 32
	v_mov_b32_e32 v150, s1
	v_mov_b32_e32 v151, s3
	v_pk_add_f32 v[150:151], s[12:13], v[150:151]
	s_nop 0
	v_add_f32_e32 v0, v150, v151
	v_fmamk_f32 v0, v0, 0x3a800000, v229
	v_mul_f32_e32 v143, 0x4f800000, v0
	v_cmp_gt_f32_e32 vcc, s59, v0
	s_nop 1
	v_cndmask_b32_e32 v0, v0, v143, vcc
	v_sqrt_f32_e32 v143, v0
	s_nop 0
	v_add_u32_e32 v150, -1, v143
	v_fma_f32 v151, -v150, v143, v0
	v_cmp_ge_f32_e64 s[12:13], 0, v151
	v_add_u32_e32 v151, 1, v143
	s_nop 0
	v_cndmask_b32_e64 v150, v143, v150, s[12:13]
	v_fma_f32 v143, -v151, v143, v0
	v_cmp_lt_f32_e64 s[12:13], 0, v143
	s_nop 1
	v_cndmask_b32_e64 v143, v150, v151, s[12:13]
	v_mul_f32_e32 v150, 0x37800000, v143
	v_cndmask_b32_e32 v143, v143, v150, vcc
	v_cmp_class_f32_e32 vcc, v0, v230
	s_nop 1
	v_cndmask_b32_e32 v0, v143, v0, vcc
	v_div_scale_f32 v143, s[12:13], v0, v0, 1.0
	v_rcp_f32_e32 v150, v143
	s_nop 0
	v_fma_f32 v151, -v143, v150, 1.0
	v_fmac_f32_e32 v150, v151, v150
	v_div_scale_f32 v151, vcc, 1.0, v0, 1.0
	v_mul_f32_e32 v152, v151, v150
	v_fma_f32 v153, -v143, v152, v151
	v_fmac_f32_e32 v152, v153, v150
	v_fma_f32 v143, -v143, v152, v151
	v_div_fmas_f32 v143, v143, v150, v152
	v_div_fixup_f32 v0, v143, v0, 1.0
	v_pk_mul_f32 v[132:133], v[132:133], v[0:1] op_sel_hi:[1,0]
	s_and_b64 vcc, exec, s[8:9]
	v_pk_mul_f32 v[152:153], v[2:3], v[132:133]
	v_pk_mul_f32 v[132:133], v[136:137], v[0:1] op_sel_hi:[1,0]
	v_bfe_u32 v143, v152, 16, 1
	v_pk_mul_f32 v[150:151], v[144:145], v[132:133]
	v_pk_mul_f32 v[132:133], v[134:135], v[0:1] op_sel_hi:[1,0]
	v_bfe_u32 v154, v153, 16, 1
	v_pk_mul_f32 v[136:137], v[8:9], v[132:133]
	v_pk_mul_f32 v[132:133], v[138:139], v[0:1] op_sel_hi:[1,0]
	v_bfe_u32 v155, v136, 16, 1
	v_pk_mul_f32 v[134:135], v[4:5], v[132:133]
	v_bfe_u32 v156, v137, 16, 1
	v_bfe_u32 v132, v135, 16, 1
	v_bfe_u32 v133, v134, 16, 1
	v_add3_u32 v156, v137, v156, s53
	v_add3_u32 v155, v136, v155, s53
	v_add3_u32 v133, v134, v133, s53
	v_add3_u32 v132, v135, v132, s53
	v_lshrrev_b32_e32 v155, 16, v155
	v_lshrrev_b32_e32 v156, 16, v156
	v_and_or_b32 v157, v132, s56, v156
	v_and_or_b32 v156, v133, s56, v155
	v_mov_b32_e32 v133, v130
	v_mov_b32_e32 v130, v129
	v_mov_b32_e32 v132, v128
	v_pk_mul_f32 v[128:129], v[130:131], v[0:1] op_sel_hi:[1,0]
	v_bfe_u32 v138, v151, 16, 1
	v_bfe_u32 v139, v150, 16, 1
	v_add3_u32 v154, v153, v154, s53
	v_add3_u32 v143, v152, v143, s53
	v_pk_mul_f32 v[130:131], v[10:11], v[128:129]
	v_mov_b32_e32 v128, v124
	v_mov_b32_e32 v129, v126
	v_add3_u32 v139, v150, v139, s53
	v_add3_u32 v138, v151, v138, s53
	v_lshrrev_b32_e32 v143, 16, v143
	v_lshrrev_b32_e32 v154, 16, v154
	v_pk_mul_f32 v[132:133], v[132:133], v[0:1] op_sel_hi:[1,0]
	v_pk_mul_f32 v[128:129], v[128:129], v[0:1] op_sel_hi:[1,0]
	v_mov_b32_e32 v126, v125
	v_and_or_b32 v155, v138, s56, v154
	v_and_or_b32 v154, v139, s56, v143
	v_lshl_add_u64 v[138:139], v[148:149], 1, s[24:25]
	v_pk_mul_f32 v[132:133], v[16:17], v[132:133]
	v_pk_mul_f32 v[128:129], v[24:25], v[128:129]
	v_pk_mul_f32 v[124:125], v[126:127], v[0:1] op_sel_hi:[1,0]
	global_store_dwordx4 v[138:139], v[154:157], off
	v_pk_mul_f32 v[124:125], v[18:19], v[124:125]
	v_bfe_u32 v148, v132, 16, 1
	v_bfe_u32 v149, v133, 16, 1
	v_bfe_u32 v154, v128, 16, 1
	v_bfe_u32 v155, v129, 16, 1
	v_bfe_u32 v0, v125, 16, 1
	v_bfe_u32 v126, v124, 16, 1
	v_bfe_u32 v127, v131, 16, 1
	v_bfe_u32 v143, v130, 16, 1
	v_add3_u32 v155, v129, v155, s53
	v_add3_u32 v154, v128, v154, s53
	v_add3_u32 v149, v133, v149, s53
	v_add3_u32 v148, v132, v148, s53
	v_add3_u32 v143, v130, v143, s53
	v_add3_u32 v127, v131, v127, s53
	v_add3_u32 v126, v124, v126, s53
	v_add3_u32 v0, v125, v0, s53
	v_lshrrev_b32_e32 v148, 16, v148
	v_lshrrev_b32_e32 v149, 16, v149
	v_lshrrev_b32_e32 v154, 16, v154
	v_lshrrev_b32_e32 v155, 16, v155
	v_and_or_b32 v157, v0, s56, v155
	v_and_or_b32 v156, v126, s56, v154
	v_and_or_b32 v155, v127, s56, v149
	v_and_or_b32 v154, v143, s56, v148
	global_store_dwordx4 v[138:139], v[154:157], off offset:1024
	s_cbranch_vccnz .LBB0_299
; __device__ __forceinline__ void row_process(const RowArgs& R, int m, int lane, const RowRaw& q, const float (&gp)[2][8], const float (&gn)[2][8], const f32x4 bf, const LAS f32x4* afl) {
;     ...
;         if (R.AF) {
;             f32x4 acc = {0.f, 0.f, 0.f, 0.f};
; #pragma unroll
;             for (int j = 0; j < 2; ++j)
; #pragma unroll
;                 for (int c = 0; c < 8; ++c) acc = acc + un[j][c] * afl[(8 * j + c) * 64 + lane];
;             acc[0] = wave_sum(acc[0]); acc[1] = wave_sum(acc[1]); acc[2] = wave_sum(acc[2]); acc[3] = wave_sum(acc[3]);
	ds_read_b128 v[100:103], v30
	ds_read_b128 v[104:107], v30 offset:1024
	ds_read_b128 v[108:111], v30 offset:2048
	ds_read_b128 v[112:115], v30 offset:3072
	s_waitcnt lgkmcnt(3)
	v_pk_fma_f32 v[126:127], v[152:153], v[100:101], 0 op_sel_hi:[0,1,0]
	v_pk_fma_f32 v[138:139], v[152:153], v[102:103], 0 op_sel_hi:[0,1,0]
	ds_read_b128 v[100:103], v30 offset:4096
	s_waitcnt lgkmcnt(3)
	v_pk_fma_f32 v[138:139], v[150:151], v[106:107], v[138:139] op_sel_hi:[0,1,1]
	v_pk_fma_f32 v[126:127], v[150:151], v[104:105], v[126:127] op_sel_hi:[0,1,1]
	ds_read_b128 v[104:107], v30 offset:5120
	s_waitcnt lgkmcnt(3)
	v_pk_fma_f32 v[138:139], v[152:153], v[110:111], v[138:139] op_sel:[1,0,0]
	v_pk_fma_f32 v[126:127], v[152:153], v[108:109], v[126:127] op_sel:[1,0,0]
	ds_read_b128 v[108:111], v30 offset:6144
	s_waitcnt lgkmcnt(3)
	v_pk_fma_f32 v[138:139], v[150:151], v[114:115], v[138:139] op_sel:[1,0,0]
	v_pk_fma_f32 v[126:127], v[150:151], v[112:113], v[126:127] op_sel:[1,0,0]
	ds_read_b128 v[112:115], v30 offset:7168
	s_waitcnt lgkmcnt(3)
	v_pk_fma_f32 v[138:139], v[136:137], v[102:103], v[138:139] op_sel_hi:[0,1,1]
	v_pk_fma_f32 v[126:127], v[136:137], v[100:101], v[126:127] op_sel_hi:[0,1,1]
	ds_read_b128 v[100:103], v30 offset:8192
	s_waitcnt lgkmcnt(3)
	v_pk_fma_f32 v[138:139], v[134:135], v[106:107], v[138:139] op_sel_hi:[0,1,1]
	v_pk_fma_f32 v[126:127], v[134:135], v[104:105], v[126:127] op_sel_hi:[0,1,1]
	ds_read_b128 v[104:107], v30 offset:9216
	s_waitcnt lgkmcnt(3)
	v_pk_fma_f32 v[138:139], v[136:137], v[110:111], v[138:139] op_sel:[1,0,0]
	v_pk_fma_f32 v[126:127], v[136:137], v[108:109], v[126:127] op_sel:[1,0,0]
	ds_read_b128 v[108:111], v30 offset:10240
	s_waitcnt lgkmcnt(3)
	v_pk_fma_f32 v[138:139], v[134:135], v[114:115], v[138:139] op_sel:[1,0,0]
	v_pk_fma_f32 v[126:127], v[134:135], v[112:113], v[126:127] op_sel:[1,0,0]
	ds_read_b128 v[112:115], v30 offset:11264
	s_waitcnt lgkmcnt(3)
	v_pk_fma_f32 v[138:139], v[132:133], v[102:103], v[138:139] op_sel_hi:[0,1,1]
	v_pk_fma_f32 v[126:127], v[132:133], v[100:101], v[126:127] op_sel_hi:[0,1,1]
	ds_read_b128 v[100:103], v30 offset:12288
	s_waitcnt lgkmcnt(3)
	v_pk_fma_f32 v[138:139], v[130:131], v[106:107], v[138:139] op_sel_hi:[0,1,1]
	v_pk_fma_f32 v[126:127], v[130:131], v[104:105], v[126:127] op_sel_hi:[0,1,1]
	ds_read_b128 v[104:107], v30 offset:13312
	s_waitcnt lgkmcnt(3)
	v_pk_fma_f32 v[138:139], v[132:133], v[110:111], v[138:139] op_sel:[1,0,0]
	v_pk_fma_f32 v[126:127], v[132:133], v[108:109], v[126:127] op_sel:[1,0,0]
	ds_read_b128 v[108:111], v30 offset:14336
	s_waitcnt lgkmcnt(3)
	v_pk_fma_f32 v[138:139], v[130:131], v[114:115], v[138:139] op_sel:[1,0,0]
	v_pk_fma_f32 v[126:127], v[130:131], v[112:113], v[126:127] op_sel:[1,0,0]
	ds_read_b128 v[112:115], v30 offset:15360
	s_waitcnt lgkmcnt(3)
	v_pk_fma_f32 v[138:139], v[128:129], v[102:103], v[138:139] op_sel_hi:[0,1,1]
	v_pk_fma_f32 v[126:127], v[128:129], v[100:101], v[126:127] op_sel_hi:[0,1,1]
	s_waitcnt lgkmcnt(2)
	v_pk_fma_f32 v[138:139], v[124:125], v[106:107], v[138:139] op_sel_hi:[0,1,1]
	v_pk_fma_f32 v[126:127], v[124:125], v[104:105], v[126:127] op_sel_hi:[0,1,1]
	s_waitcnt lgkmcnt(1)
	v_pk_fma_f32 v[138:139], v[128:129], v[110:111], v[138:139] op_sel:[1,0,0]
	v_pk_fma_f32 v[126:127], v[128:129], v[108:109], v[126:127] op_sel:[1,0,0]
	s_waitcnt lgkmcnt(0)
	v_pk_fma_f32 v[138:139], v[124:125], v[114:115], v[138:139] op_sel:[1,0,0]
	v_pk_fma_f32 v[126:127], v[124:125], v[112:113], v[126:127] op_sel:[1,0,0]
	v_mov_b32_e32 v124, v126
	v_mov_b32_e32 v125, v127
	v_mov_b32_e32 v128, v138
	v_mov_b32_e32 v129, v139
	s_nop 1
	v_add_f32_dpp v0, v124, v124 quad_perm:[1,0,3,2] row_mask:0xf bank_mask:0xf bound_ctrl:1
	s_nop 1
	v_add_f32_dpp v0, v0, v0 quad_perm:[2,3,0,1] row_mask:0xf bank_mask:0xf bound_ctrl:1
	s_nop 1
	v_add_f32_dpp v0, v0, v0 row_half_mirror row_mask:0xf bank_mask:0xf bound_ctrl:1
	s_nop 1
	v_add_f32_dpp v0, v0, v0 row_mirror row_mask:0xf bank_mask:0xf bound_ctrl:1
	s_nop 0
	v_readlane_b32 s68, v0, 0
	v_readlane_b32 s1, v0, 16
	v_readlane_b32 s69, v0, 32
	v_readlane_b32 s3, v0, 48
	v_add_f32_dpp v0, v125, v125 quad_perm:[1,0,3,2] row_mask:0xf bank_mask:0xf bound_ctrl:1
	s_nop 1
	v_add_f32_dpp v0, v0, v0 quad_perm:[2,3,0,1] row_mask:0xf bank_mask:0xf bound_ctrl:1
	s_nop 1
	v_add_f32_dpp v0, v0, v0 row_half_mirror row_mask:0xf bank_mask:0xf bound_ctrl:1
	s_nop 1
	v_add_f32_dpp v0, v0, v0 row_mirror row_mask:0xf bank_mask:0xf bound_ctrl:1
	s_nop 0
	v_readlane_b32 s14, v0, 0
	v_readlane_b32 s4, v0, 16
	v_readlane_b32 s15, v0, 32
	v_readlane_b32 s18, v0, 48
	v_add_f32_dpp v0, v128, v128 quad_perm:[1,0,3,2] row_mask:0xf bank_mask:0xf bound_ctrl:1
	s_nop 1
	v_add_f32_dpp v0, v0, v0 quad_perm:[2,3,0,1] row_mask:0xf bank_mask:0xf bound_ctrl:1
	s_nop 1
	v_add_f32_dpp v0, v0, v0 row_half_mirror row_mask:0xf bank_mask:0xf bound_ctrl:1
	s_nop 1
	v_add_f32_dpp v0, v0, v0 row_mirror row_mask:0xf bank_mask:0xf bound_ctrl:1
	s_nop 0
	v_readlane_b32 s70, v0, 0
	v_readlane_b32 s19, v0, 16
	v_readlane_b32 s71, v0, 32
	v_readlane_b32 s23, v0, 48
	v_add_f32_dpp v0, v129, v129 quad_perm:[1,0,3,2] row_mask:0xf bank_mask:0xf bound_ctrl:1
	s_nop 1
	v_add_f32_dpp v0, v0, v0 quad_perm:[2,3,0,1] row_mask:0xf bank_mask:0xf bound_ctrl:1
	s_nop 1
	v_add_f32_dpp v0, v0, v0 row_half_mirror row_mask:0xf bank_mask:0xf bound_ctrl:1
	s_nop 1
	v_add_f32_dpp v0, v0, v0 row_mirror row_mask:0xf bank_mask:0xf bound_ctrl:1
	s_nop 0
	v_readlane_b32 s48, v0, 0
	v_readlane_b32 s33, v0, 16
	v_readlane_b32 s49, v0, 32
	v_readlane_b32 s51, v0, 48
	s_and_saveexec_b64 s[12:13], s[10:11]
	s_cbranch_execz .LBB0_298
; __device__ __forceinline__ float log_sigmoid_f(float x) { return fminf(x, 0.f) - log1pf(expf(-fabsf(x))); }
; __device__ __forceinline__ void row_process(const RowArgs& R, int m, int lane, const RowRaw& q, const float (&gp)[2][8], const float (&gn)[2][8], const f32x4 bf, const LAS f32x4* afl) {
;     ...
;             acc[0] = wave_sum(acc[0]); acc[1] = wave_sum(acc[1]); acc[2] = wave_sum(acc[2]); acc[3] = wave_sum(acc[3]);
;             if (lane == 0) { f32x4 o; o[0] = log_sigmoid_f(acc[0] + bf[0]); o[1] = log_sigmoid_f(acc[1] + bf[1]); o[2] = log_sigmoid_f(acc[2] + bf[2]); o[3] = log_sigmoid_f(acc[3] + bf[3]); *(f32x4*)(R.LOGF + (size_t)m * 4) = o; }
	v_mov_b32_e32 v126, s1
	v_mov_b32_e32 v127, s3
	v_pk_add_f32 v[126:127], s[68:69], v[126:127]
	v_mov_b32_e32 v124, s33
	v_add_f32_e32 v126, v126, v127
	v_add_f32_e32 v126, v32, v126
	v_mul_f32_e64 v127, |v126|, s22
	v_fma_f32 v128, |v126|, s22, -v127
	v_rndne_f32_e32 v129, v127
	v_fma_f32 v128, |v126|, s29, v128
	v_sub_f32_e32 v127, v127, v129
	v_add_f32_e32 v127, v127, v128
	v_exp_f32_e32 v127, v127
	v_cvt_i32_f32_e32 v128, v129
	v_mov_b32_e32 v125, s51
	v_pk_add_f32 v[124:125], s[48:49], v[124:125]
	v_cmp_ngt_f32_e64 vcc, |v126|, s55
	v_add_f32_e32 v0, v124, v125
	v_mov_b32_e32 v124, s19
	v_mov_b32_e32 v125, s23
	v_ldexp_f32 v127, v127, v128
	s_mov_b32 s1, 0xc2b17218
	v_pk_add_f32 v[124:125], s[70:71], v[124:125]
	v_cndmask_b32_e32 v127, 0, v127, vcc
	v_cmp_nlt_f32_e64 vcc, |v126|, s1
	v_add_f32_e32 v143, v124, v125
	v_mov_b32_e32 v124, s4
	v_mov_b32_e32 v125, s18
	v_cndmask_b32_e32 v164, v235, v127, vcc
	v_pk_add_f32 v[124:125], s[14:15], v[124:125]
	v_add_f32_e32 v128, 1.0, v164
	v_add_f32_e32 v125, v124, v125
	v_min_f32_e32 v124, 0, v126
	v_add_f32_e32 v126, -1.0, v128
	v_sub_f32_e32 v127, v126, v128
	v_add_f32_e32 v131, v33, v125
	v_add_f32_e32 v127, 1.0, v127
	v_sub_f32_e32 v126, v164, v126
	v_mul_f32_e64 v125, |v131|, s22
	v_add_f32_e32 v129, v126, v127
	v_fma_f32 v126, |v131|, s22, -v125
	v_rndne_f32_e32 v127, v125
	v_fma_f32 v126, |v131|, s29, v126
	v_sub_f32_e32 v125, v125, v127
	v_add_f32_e32 v125, v125, v126
	v_exp_f32_e32 v132, v125
	v_cvt_i32_f32_e32 v133, v127
	v_cvt_f64_f32_e32 v[126:127], v128
	v_frexp_exp_i32_f64_e32 v134, v[126:127]
	v_cmp_ngt_f32_e64 vcc, |v131|, s55
	v_ldexp_f32 v126, v132, v133
	v_min_f32_e32 v125, 0, v131
	v_cndmask_b32_e32 v126, 0, v126, vcc
	v_cmp_nlt_f32_e64 vcc, |v131|, s1
	s_mov_b32 s4, 0x3f2aaaab
	v_frexp_mant_f32_e32 v130, v128
	v_cndmask_b32_e32 v165, v235, v126, vcc
	v_add_f32_e32 v131, 1.0, v165
	v_add_f32_e32 v126, -1.0, v131
	v_sub_f32_e32 v127, v126, v131
	v_add_f32_e32 v127, 1.0, v127
	v_sub_f32_e32 v126, v165, v126
	v_add_f32_e32 v132, v126, v127
	v_frexp_mant_f32_e32 v133, v131
	v_cvt_f64_f32_e32 v[126:127], v131
	v_frexp_exp_i32_f64_e32 v126, v[126:127]
	v_cmp_gt_f32_e32 vcc, s4, v133
	s_mov_b32 s14, 0x3ecc95a3
	s_mov_b32 s18, 0x3e9b6dac
	v_subbrev_co_u32_e32 v154, vcc, 0, v126, vcc
	v_cmp_gt_f32_e32 vcc, s4, v130
	s_mov_b32 s48, 0x3f2aaada
	s_mov_b32 s68, 0x3f317218
	v_subbrev_co_u32_e32 v155, vcc, 0, v134, vcc
	v_sub_u32_e32 v127, 0, v155
	v_ldexp_f32 v126, v128, v127
	v_ldexp_f32 v128, v129, v127
	v_sub_u32_e32 v129, 0, v154
	v_ldexp_f32 v127, v131, v129
	v_pk_add_f32 v[130:131], v[126:127], 1.0 op_sel_hi:[1,0]
	v_ldexp_f32 v129, v132, v129
	v_pk_add_f32 v[132:133], v[130:131], -1.0 op_sel_hi:[1,0]
	v_pk_add_f32 v[138:139], v[126:127], -1.0 op_sel_hi:[1,0]
	v_pk_add_f32 v[132:133], v[126:127], v[132:133] neg_lo:[0,1] neg_hi:[0,1]
	v_pk_add_f32 v[148:149], v[138:139], 1.0 op_sel_hi:[1,0]
	v_pk_add_f32 v[132:133], v[128:129], v[132:133]
	v_pk_add_f32 v[126:127], v[126:127], v[148:149] neg_lo:[0,1] neg_hi:[0,1]
	v_pk_add_f32 v[134:135], v[130:131], v[132:133]
	v_pk_add_f32 v[126:127], v[128:129], v[126:127]
	v_rcp_f32_e32 v136, v134
	v_rcp_f32_e32 v137, v135
	v_pk_add_f32 v[128:129], v[138:139], v[126:127]
	v_pk_add_f32 v[130:131], v[130:131], v[134:135] neg_lo:[0,1] neg_hi:[0,1]
	v_pk_add_f32 v[138:139], v[138:139], v[128:129] neg_lo:[0,1] neg_hi:[0,1]
	v_pk_add_f32 v[130:131], v[132:133], v[130:131]
	v_pk_mul_f32 v[132:133], v[128:129], v[136:137]
	v_pk_add_f32 v[126:127], v[126:127], v[138:139]
	v_pk_mul_f32 v[138:139], v[134:135], v[132:133]
	s_mov_b32 s70, 0xb102e308
	v_pk_fma_f32 v[148:149], v[132:133], v[134:135], v[138:139] neg_lo:[0,0,1] neg_hi:[0,0,1]
	s_mov_b32 s3, 0x7f800000
	v_pk_fma_f32 v[148:149], v[132:133], v[130:131], v[148:149]
	v_cmp_neq_f32_e32 vcc, s3, v164
	v_pk_add_f32 v[150:151], v[138:139], v[148:149]
	v_add_f32_e32 v0, v35, v0
	v_pk_add_f32 v[152:153], v[128:129], v[150:151] neg_lo:[0,1] neg_hi:[0,1]
	v_pk_add_f32 v[138:139], v[150:151], v[138:139] neg_lo:[0,1] neg_hi:[0,1]
	v_pk_add_f32 v[128:129], v[128:129], v[152:153] neg_lo:[0,1] neg_hi:[0,1]
	s_nop 0
	v_pk_add_f32 v[128:129], v[128:129], v[150:151] neg_lo:[0,1] neg_hi:[0,1]
	s_nop 0
	v_pk_add_f32 v[126:127], v[126:127], v[128:129]
	v_pk_add_f32 v[128:129], v[138:139], v[148:149] neg_lo:[0,1] neg_hi:[0,1]
	s_nop 0
	v_pk_add_f32 v[126:127], v[128:129], v[126:127]
	s_nop 0
	v_pk_add_f32 v[128:129], v[152:153], v[126:127]
	s_nop 0
	v_pk_mul_f32 v[138:139], v[136:137], v[128:129]
	s_nop 0
	v_pk_mul_f32 v[148:149], v[134:135], v[138:139]
	s_nop 0
	v_pk_fma_f32 v[134:135], v[138:139], v[134:135], v[148:149] neg_lo:[0,0,1] neg_hi:[0,0,1]
	s_nop 0
	v_pk_fma_f32 v[130:131], v[138:139], v[130:131], v[134:135]
	v_pk_add_f32 v[134:135], v[152:153], v[128:129] neg_lo:[0,1] neg_hi:[0,1]
	s_nop 0
	v_pk_add_f32 v[126:127], v[126:127], v[134:135]
	v_pk_add_f32 v[134:135], v[148:149], v[130:131]
	s_nop 0
	v_pk_add_f32 v[150:151], v[128:129], v[134:135] neg_lo:[0,1] neg_hi:[0,1]
	v_pk_add_f32 v[148:149], v[134:135], v[148:149] neg_lo:[0,1] neg_hi:[0,1]
	v_pk_add_f32 v[128:129], v[128:129], v[150:151] neg_lo:[0,1] neg_hi:[0,1]
	s_nop 0
	v_pk_add_f32 v[128:129], v[128:129], v[134:135] neg_lo:[0,1] neg_hi:[0,1]
	v_cvt_f32_i32_e32 v135, v154
	v_pk_add_f32 v[126:127], v[126:127], v[128:129]
	v_pk_add_f32 v[128:129], v[148:149], v[130:131] neg_lo:[0,1] neg_hi:[0,1]
	v_cvt_f32_i32_e32 v134, v155
	v_pk_add_f32 v[126:127], v[128:129], v[126:127]
	v_pk_add_f32 v[128:129], v[132:133], v[138:139]
	v_pk_add_f32 v[126:127], v[150:151], v[126:127]
	v_pk_add_f32 v[130:131], v[128:129], v[132:133] neg_lo:[0,1] neg_hi:[0,1]
; __device__ __forceinline__ float log_sigmoid_f(float x) { return fminf(x, 0.f) - log1pf(expf(-fabsf(x))); }
; __device__ __forceinline__ void row_process(const RowArgs& R, int m, int lane, const RowRaw& q, const float (&gp)[2][8], const float (&gn)[2][8], const f32x4 bf, const LAS f32x4* afl) {
;     ...
;             if (lane == 0) { f32x4 o; o[0] = log_sigmoid_f(acc[0] + bf[0]); o[1] = log_sigmoid_f(acc[1] + bf[1]); o[2] = log_sigmoid_f(acc[2] + bf[2]); o[3] = log_sigmoid_f(acc[3] + bf[3]); *(f32x4*)(R.LOGF + (size_t)m * 4) = o; }
	v_pk_mul_f32 v[126:127], v[136:137], v[126:127]
	v_pk_add_f32 v[130:131], v[138:139], v[130:131] neg_lo:[0,1] neg_hi:[0,1]
	v_mov_b64_e32 v[136:137], s[14:15]
	v_pk_add_f32 v[126:127], v[130:131], v[126:127]
	v_pk_mul_f32 v[148:149], v[134:135], s[68:69] op_sel_hi:[1,0]
	v_pk_add_f32 v[130:131], v[128:129], v[126:127]
	v_pk_fma_f32 v[150:151], v[134:135], s[68:69], v[148:149] op_sel_hi:[1,0,1] neg_lo:[0,0,1] neg_hi:[0,0,1]
	v_pk_mul_f32 v[132:133], v[130:131], v[130:131]
	v_pk_add_f32 v[128:129], v[130:131], v[128:129] neg_lo:[0,1] neg_hi:[0,1]
	v_pk_fma_f32 v[138:139], v[132:133], s[18:19], v[136:137] op_sel_hi:[1,0,0]
	v_pk_add_f32 v[126:127], v[126:127], v[128:129] neg_lo:[0,1] neg_hi:[0,1]
	v_ldexp_f32 v128, v130, 1
	v_pk_fma_f32 v[138:139], v[132:133], v[138:139], s[48:49] op_sel_hi:[1,1,0]
	v_ldexp_f32 v129, v131, 1
	v_pk_mul_f32 v[130:131], v[130:131], v[132:133]
	v_mov_b32_e32 v153, v129
	v_pk_mul_f32 v[130:131], v[130:131], v[138:139]
	v_ldexp_f32 v126, v126, 1
	v_pk_add_f32 v[132:133], v[128:129], v[130:131]
	v_pk_fma_f32 v[134:135], v[134:135], s[70:71], v[150:151] op_sel_hi:[1,0,1]
	v_pk_add_f32 v[128:129], v[132:133], v[128:129] neg_lo:[0,1] neg_hi:[0,1]
	v_ldexp_f32 v127, v127, 1
	v_pk_add_f32 v[128:129], v[130:131], v[128:129] neg_lo:[0,1] neg_hi:[0,1]
	v_mov_b32_e32 v138, v148
	v_mov_b32_e32 v139, v131
	v_mov_b32_e32 v152, v134
	v_pk_add_f32 v[130:131], v[126:127], v[128:129]
	v_mov_b32_e32 v128, v148
	v_mov_b32_e32 v126, v134
	v_pk_add_f32 v[138:139], v[138:139], v[152:153]
	v_pk_add_f32 v[152:153], v[128:129], v[126:127]
	v_mov_b32_e32 v126, v132
	v_mov_b32_e32 v128, v130
	v_pk_add_f32 v[150:151], v[148:149], v[134:135]
	v_pk_add_f32 v[126:127], v[126:127], v[128:129]
	v_pk_add_f32 v[128:129], v[132:133], v[130:131]
	v_mov_b32_e32 v154, v150
	v_mov_b32_e32 v155, v149
	v_mov_b32_e32 v156, v128
	v_mov_b32_e32 v157, v135
	v_pk_add_f32 v[126:127], v[138:139], v[126:127]
	v_pk_add_f32 v[138:139], v[150:151], v[128:129]
	v_pk_add_f32 v[158:159], v[154:155], v[156:157]
	v_mov_b32_e32 v160, v128
	v_mov_b32_e32 v161, v139
	v_mov_b32_e32 v162, v132
	v_mov_b32_e32 v163, v151
	v_pk_add_f32 v[154:155], v[158:159], v[154:155] neg_lo:[0,1] neg_hi:[0,1]
	v_pk_add_f32 v[160:161], v[160:161], v[162:163] neg_lo:[0,1] neg_hi:[0,1]
	v_pk_add_f32 v[158:159], v[150:151], v[148:149] neg_lo:[0,1] neg_hi:[0,1]
	v_pk_add_f32 v[156:157], v[156:157], v[154:155] neg_lo:[0,1] neg_hi:[0,1]
	v_mov_b32_e32 v162, v150
	v_mov_b32_e32 v163, v139
	v_mov_b32_e32 v149, v161
	v_mov_b32_e32 v155, v133
	v_pk_add_f32 v[132:133], v[128:129], v[132:133] neg_lo:[0,1] neg_hi:[0,1]
	v_pk_add_f32 v[148:149], v[162:163], v[148:149] neg_lo:[0,1] neg_hi:[0,1]
	v_pk_add_f32 v[158:159], v[134:135], v[158:159] neg_lo:[0,1] neg_hi:[0,1]
	v_pk_add_f32 v[126:127], v[126:127], v[154:155] neg_lo:[0,1] neg_hi:[0,1]
	v_pk_add_f32 v[132:133], v[130:131], v[132:133] neg_lo:[0,1] neg_hi:[0,1]
	v_mov_b32_e32 v135, v151
	v_mov_b32_e32 v131, v129
	v_pk_add_f32 v[126:127], v[152:153], v[126:127] neg_lo:[0,1] neg_hi:[0,1]
	v_pk_add_f32 v[134:135], v[134:135], v[148:149] neg_lo:[0,1] neg_hi:[0,1]
	v_pk_add_f32 v[128:129], v[130:131], v[160:161] neg_lo:[0,1] neg_hi:[0,1]
	v_pk_add_f32 v[148:149], v[156:157], v[126:127]
	v_pk_add_f32 v[130:131], v[128:129], v[134:135]
	v_mov_b32_e32 v129, v127
	v_pk_add_f32 v[126:127], v[158:159], v[128:129]
	v_mov_b32_e32 v135, v157
	v_pk_add_f32 v[126:127], v[126:127], v[134:135] neg_lo:[0,1] neg_hi:[0,1]
	v_mov_b32_e32 v128, v130
	v_mov_b32_e32 v129, v149
	v_pk_add_f32 v[128:129], v[128:129], v[126:127] neg_lo:[0,1] neg_hi:[0,1]
	v_pk_add_f32 v[126:127], v[132:133], v[126:127] neg_lo:[0,1] neg_hi:[0,1]
	v_pk_add_f32 v[128:129], v[134:135], v[128:129] neg_lo:[0,1] neg_hi:[0,1]
	s_mov_b32 s14, 0x33800000
	v_pk_add_f32 v[126:127], v[126:127], v[128:129]
	v_pk_add_f32 v[128:129], v[148:149], v[130:131]
	s_nop 0
	v_pk_add_f32 v[130:131], v[138:139], v[128:129]
	s_nop 0
	v_pk_add_f32 v[132:133], v[130:131], v[138:139] neg_lo:[0,1] neg_hi:[0,1]
	s_nop 0
	v_pk_add_f32 v[128:129], v[128:129], v[132:133] neg_lo:[0,1] neg_hi:[0,1]
	s_nop 0
	v_pk_add_f32 v[126:127], v[126:127], v[128:129]
	v_add_f32_e32 v128, v34, v143
	v_mul_f32_e64 v129, |v128|, s22
	v_pk_add_f32 v[126:127], v[130:131], v[126:127]
	v_fma_f32 v130, |v128|, s22, -v129
	v_rndne_f32_e32 v131, v129
	v_fma_f32 v130, |v128|, s29, v130
	v_sub_f32_e32 v129, v129, v131
	v_add_f32_e32 v129, v129, v130
	v_cndmask_b32_e32 v126, v235, v126, vcc
	v_cmp_neq_f32_e32 vcc, s3, v165
	v_exp_f32_e32 v129, v129
	v_cvt_i32_f32_e32 v130, v131
	v_cndmask_b32_e32 v127, v235, v127, vcc
	v_cmp_lt_f32_e64 vcc, |v165|, s14
	s_nop 1
	v_cndmask_b32_e32 v127, v127, v165, vcc
	v_cmp_lt_f32_e64 vcc, |v164|, s14
	s_nop 1
	v_cndmask_b32_e32 v126, v126, v164, vcc
	v_pk_add_f32 v[124:125], v[124:125], v[126:127] neg_lo:[0,1] neg_hi:[0,1]
	v_ldexp_f32 v127, v129, v130
	v_cmp_ngt_f32_e64 vcc, |v128|, s55
	v_min_f32_e32 v126, 0, v128
	s_nop 0
	v_cndmask_b32_e32 v127, 0, v127, vcc
	v_cmp_nlt_f32_e64 vcc, |v128|, s1
	s_nop 1
	v_cndmask_b32_e32 v143, v235, v127, vcc
	v_add_f32_e32 v130, 1.0, v143
	v_add_f32_e32 v127, -1.0, v130
	v_sub_f32_e32 v128, v127, v130
	v_add_f32_e32 v128, 1.0, v128
	v_sub_f32_e32 v127, v143, v127
	v_add_f32_e32 v131, v127, v128
	v_mul_f32_e64 v127, |v0|, s22
	v_fma_f32 v128, |v0|, s22, -v127
	v_rndne_f32_e32 v129, v127
	v_fma_f32 v128, |v0|, s29, v128
	v_sub_f32_e32 v127, v127, v129
	v_add_f32_e32 v127, v127, v128
	v_exp_f32_e32 v133, v127
	v_cvt_i32_f32_e32 v134, v129
	v_cvt_f64_f32_e32 v[128:129], v130
	v_frexp_exp_i32_f64_e32 v135, v[128:129]
	v_cmp_ngt_f32_e64 vcc, |v0|, s55
	v_ldexp_f32 v128, v133, v134
; __device__ __forceinline__ float log_sigmoid_f(float x) { return fminf(x, 0.f) - log1pf(expf(-fabsf(x))); }
; __device__ __forceinline__ void row_process(const RowArgs& R, int m, int lane, const RowRaw& q, const float (&gp)[2][8], const float (&gn)[2][8], const f32x4 bf, const LAS f32x4* afl) {
;     ...
;             if (lane == 0) { f32x4 o; o[0] = log_sigmoid_f(acc[0] + bf[0]); o[1] = log_sigmoid_f(acc[1] + bf[1]); o[2] = log_sigmoid_f(acc[2] + bf[2]); o[3] = log_sigmoid_f(acc[3] + bf[3]); *(f32x4*)(R.LOGF + (size_t)m * 4) = o; }
	v_min_f32_e32 v127, 0, v0
	v_cndmask_b32_e32 v128, 0, v128, vcc
	v_cmp_nlt_f32_e64 vcc, |v0|, s1
	v_frexp_mant_f32_e32 v132, v130
	s_nop 0
	v_cndmask_b32_e32 v0, v235, v128, vcc
	v_add_f32_e32 v133, 1.0, v0
	v_add_f32_e32 v128, -1.0, v133
	v_sub_f32_e32 v129, v128, v133
	v_add_f32_e32 v129, 1.0, v129
	v_sub_f32_e32 v128, v0, v128
	v_add_f32_e32 v134, v128, v129
	v_frexp_mant_f32_e32 v138, v133
	v_cvt_f64_f32_e32 v[128:129], v133
	v_frexp_exp_i32_f64_e32 v128, v[128:129]
	v_cmp_gt_f32_e32 vcc, s4, v138
	s_nop 1
	v_subbrev_co_u32_e32 v158, vcc, 0, v128, vcc
	v_cmp_gt_f32_e32 vcc, s4, v132
	s_nop 1
	v_subbrev_co_u32_e32 v159, vcc, 0, v135, vcc
	v_sub_u32_e32 v129, 0, v159
	v_ldexp_f32 v128, v130, v129
	v_ldexp_f32 v130, v131, v129
	v_sub_u32_e32 v131, 0, v158
	v_ldexp_f32 v129, v133, v131
	v_pk_add_f32 v[132:133], v[128:129], 1.0 op_sel_hi:[1,0]
	v_ldexp_f32 v131, v134, v131
	v_pk_add_f32 v[134:135], v[132:133], -1.0 op_sel_hi:[1,0]
	v_pk_add_f32 v[150:151], v[128:129], -1.0 op_sel_hi:[1,0]
	v_pk_add_f32 v[134:135], v[128:129], v[134:135] neg_lo:[0,1] neg_hi:[0,1]
	v_pk_add_f32 v[152:153], v[150:151], 1.0 op_sel_hi:[1,0]
	v_pk_add_f32 v[134:135], v[130:131], v[134:135]
	v_pk_add_f32 v[128:129], v[128:129], v[152:153] neg_lo:[0,1] neg_hi:[0,1]
	v_pk_add_f32 v[138:139], v[132:133], v[134:135]
	v_pk_add_f32 v[128:129], v[130:131], v[128:129]
	v_rcp_f32_e32 v148, v138
	v_rcp_f32_e32 v149, v139
	v_pk_add_f32 v[130:131], v[150:151], v[128:129]
	v_pk_add_f32 v[132:133], v[132:133], v[138:139] neg_lo:[0,1] neg_hi:[0,1]
	v_pk_add_f32 v[150:151], v[150:151], v[130:131] neg_lo:[0,1] neg_hi:[0,1]
	v_pk_add_f32 v[132:133], v[134:135], v[132:133]
	v_pk_mul_f32 v[134:135], v[130:131], v[148:149]
	v_pk_add_f32 v[128:129], v[128:129], v[150:151]
	v_pk_mul_f32 v[150:151], v[138:139], v[134:135]
	v_cmp_neq_f32_e32 vcc, s3, v143
	v_pk_fma_f32 v[152:153], v[134:135], v[138:139], v[150:151] neg_lo:[0,0,1] neg_hi:[0,0,1]
	s_nop 0
	v_pk_fma_f32 v[152:153], v[134:135], v[132:133], v[152:153]
	s_nop 0
	v_pk_add_f32 v[154:155], v[150:151], v[152:153]
	s_nop 0
	v_pk_add_f32 v[156:157], v[130:131], v[154:155] neg_lo:[0,1] neg_hi:[0,1]
	v_pk_add_f32 v[150:151], v[154:155], v[150:151] neg_lo:[0,1] neg_hi:[0,1]
	v_pk_add_f32 v[130:131], v[130:131], v[156:157] neg_lo:[0,1] neg_hi:[0,1]
	s_nop 0
	v_pk_add_f32 v[130:131], v[130:131], v[154:155] neg_lo:[0,1] neg_hi:[0,1]
	s_nop 0
	v_pk_add_f32 v[128:129], v[128:129], v[130:131]
	v_pk_add_f32 v[130:131], v[150:151], v[152:153] neg_lo:[0,1] neg_hi:[0,1]
	s_nop 0
	v_pk_add_f32 v[128:129], v[130:131], v[128:129]
	s_nop 0
	v_pk_add_f32 v[130:131], v[156:157], v[128:129]
	s_nop 0
	v_pk_mul_f32 v[150:151], v[148:149], v[130:131]
	s_nop 0
	v_pk_mul_f32 v[152:153], v[138:139], v[150:151]
	s_nop 0
	v_pk_fma_f32 v[138:139], v[150:151], v[138:139], v[152:153] neg_lo:[0,0,1] neg_hi:[0,0,1]
	s_nop 0
	v_pk_fma_f32 v[132:133], v[150:151], v[132:133], v[138:139]
	v_pk_add_f32 v[138:139], v[156:157], v[130:131] neg_lo:[0,1] neg_hi:[0,1]
	s_nop 0
	v_pk_add_f32 v[128:129], v[128:129], v[138:139]
	v_pk_add_f32 v[138:139], v[152:153], v[132:133]
	s_nop 0
	v_pk_add_f32 v[154:155], v[130:131], v[138:139] neg_lo:[0,1] neg_hi:[0,1]
	v_pk_add_f32 v[152:153], v[138:139], v[152:153] neg_lo:[0,1] neg_hi:[0,1]
	v_pk_add_f32 v[130:131], v[130:131], v[154:155] neg_lo:[0,1] neg_hi:[0,1]
	s_nop 0
	v_pk_add_f32 v[130:131], v[130:131], v[138:139] neg_lo:[0,1] neg_hi:[0,1]
	s_nop 0
	v_pk_add_f32 v[128:129], v[128:129], v[130:131]
	v_pk_add_f32 v[130:131], v[152:153], v[132:133] neg_lo:[0,1] neg_hi:[0,1]
	s_nop 0
	v_pk_add_f32 v[128:129], v[130:131], v[128:129]
	v_pk_add_f32 v[130:131], v[134:135], v[150:151]
	v_pk_add_f32 v[128:129], v[154:155], v[128:129]
	v_pk_add_f32 v[132:133], v[130:131], v[134:135] neg_lo:[0,1] neg_hi:[0,1]
	v_pk_mul_f32 v[128:129], v[148:149], v[128:129]
	v_pk_add_f32 v[132:133], v[150:151], v[132:133] neg_lo:[0,1] neg_hi:[0,1]
	v_cvt_f32_i32_e32 v135, v158
	v_pk_add_f32 v[128:129], v[132:133], v[128:129]
	v_cvt_f32_i32_e32 v134, v159
	v_pk_add_f32 v[132:133], v[130:131], v[128:129]
	v_pk_mul_f32 v[148:149], v[134:135], s[68:69] op_sel_hi:[1,0]
	v_pk_mul_f32 v[138:139], v[132:133], v[132:133]
	v_pk_add_f32 v[130:131], v[132:133], v[130:131] neg_lo:[0,1] neg_hi:[0,1]
; __device__ __forceinline__ float log_sigmoid_f(float x) { return fminf(x, 0.f) - log1pf(expf(-fabsf(x))); }
; __device__ __forceinline__ void row_process(const RowArgs& R, int m, int lane, const RowRaw& q, const float (&gp)[2][8], const float (&gn)[2][8], const f32x4 bf, const LAS f32x4* afl) {
;     ...
;             if (lane == 0) { f32x4 o; o[0] = log_sigmoid_f(acc[0] + bf[0]); o[1] = log_sigmoid_f(acc[1] + bf[1]); o[2] = log_sigmoid_f(acc[2] + bf[2]); o[3] = log_sigmoid_f(acc[3] + bf[3]); *(f32x4*)(R.LOGF + (size_t)m * 4) = o; }
	v_pk_fma_f32 v[136:137], v[138:139], s[18:19], v[136:137] op_sel_hi:[1,0,0]
	v_pk_add_f32 v[128:129], v[128:129], v[130:131] neg_lo:[0,1] neg_hi:[0,1]
	v_ldexp_f32 v130, v132, 1
	v_pk_fma_f32 v[136:137], v[138:139], v[136:137], s[48:49] op_sel_hi:[1,1,0]
	v_ldexp_f32 v131, v133, 1
	v_pk_mul_f32 v[132:133], v[132:133], v[138:139]
	v_pk_fma_f32 v[150:151], v[134:135], s[68:69], v[148:149] op_sel_hi:[1,0,1] neg_lo:[0,0,1] neg_hi:[0,0,1]
	v_pk_mul_f32 v[132:133], v[132:133], v[136:137]
	v_mov_b32_e32 v153, v131
	v_pk_add_f32 v[136:137], v[130:131], v[132:133]
	v_ldexp_f32 v128, v128, 1
	v_pk_add_f32 v[130:131], v[136:137], v[130:131] neg_lo:[0,1] neg_hi:[0,1]
	v_pk_fma_f32 v[134:135], v[134:135], s[70:71], v[150:151] op_sel_hi:[1,0,1]
	v_ldexp_f32 v129, v129, 1
	v_pk_add_f32 v[130:131], v[132:133], v[130:131] neg_lo:[0,1] neg_hi:[0,1]
	v_mov_b32_e32 v138, v148
	v_mov_b32_e32 v139, v133
	v_mov_b32_e32 v152, v134
	v_pk_add_f32 v[132:133], v[128:129], v[130:131]
	v_mov_b32_e32 v130, v148
	v_mov_b32_e32 v128, v134
	v_pk_add_f32 v[138:139], v[138:139], v[152:153]
	v_pk_add_f32 v[152:153], v[130:131], v[128:129]
	v_mov_b32_e32 v128, v136
	v_mov_b32_e32 v130, v132
	v_pk_add_f32 v[150:151], v[148:149], v[134:135]
	v_pk_add_f32 v[128:129], v[128:129], v[130:131]
	v_pk_add_f32 v[130:131], v[136:137], v[132:133]
	v_mov_b32_e32 v154, v150
	v_mov_b32_e32 v155, v149
	v_mov_b32_e32 v156, v130
	v_mov_b32_e32 v157, v135
	v_pk_add_f32 v[128:129], v[138:139], v[128:129]
	v_pk_add_f32 v[138:139], v[150:151], v[130:131]
	v_pk_add_f32 v[158:159], v[154:155], v[156:157]
	v_mov_b32_e32 v160, v130
	v_mov_b32_e32 v161, v139
	v_mov_b32_e32 v162, v136
	v_mov_b32_e32 v163, v151
	v_pk_add_f32 v[154:155], v[158:159], v[154:155] neg_lo:[0,1] neg_hi:[0,1]
	v_pk_add_f32 v[160:161], v[160:161], v[162:163] neg_lo:[0,1] neg_hi:[0,1]
	v_pk_add_f32 v[158:159], v[150:151], v[148:149] neg_lo:[0,1] neg_hi:[0,1]
	v_pk_add_f32 v[156:157], v[156:157], v[154:155] neg_lo:[0,1] neg_hi:[0,1]
	v_mov_b32_e32 v162, v150
	v_mov_b32_e32 v163, v139
	v_mov_b32_e32 v149, v161
	v_mov_b32_e32 v155, v137
	v_pk_add_f32 v[136:137], v[130:131], v[136:137] neg_lo:[0,1] neg_hi:[0,1]
	v_pk_add_f32 v[148:149], v[162:163], v[148:149] neg_lo:[0,1] neg_hi:[0,1]
	v_pk_add_f32 v[158:159], v[134:135], v[158:159] neg_lo:[0,1] neg_hi:[0,1]
	v_pk_add_f32 v[128:129], v[128:129], v[154:155] neg_lo:[0,1] neg_hi:[0,1]
	v_pk_add_f32 v[136:137], v[132:133], v[136:137] neg_lo:[0,1] neg_hi:[0,1]
	v_mov_b32_e32 v135, v151
	v_mov_b32_e32 v133, v131
	v_pk_add_f32 v[128:129], v[152:153], v[128:129] neg_lo:[0,1] neg_hi:[0,1]
	v_pk_add_f32 v[134:135], v[134:135], v[148:149] neg_lo:[0,1] neg_hi:[0,1]
	v_pk_add_f32 v[130:131], v[132:133], v[160:161] neg_lo:[0,1] neg_hi:[0,1]
	v_pk_add_f32 v[148:149], v[156:157], v[128:129]
	v_pk_add_f32 v[132:133], v[130:131], v[134:135]
	v_mov_b32_e32 v131, v129
	v_pk_add_f32 v[128:129], v[158:159], v[130:131]
	v_mov_b32_e32 v135, v157
	v_pk_add_f32 v[128:129], v[128:129], v[134:135] neg_lo:[0,1] neg_hi:[0,1]
	v_mov_b32_e32 v130, v132
	v_mov_b32_e32 v131, v149
	v_pk_add_f32 v[130:131], v[130:131], v[128:129] neg_lo:[0,1] neg_hi:[0,1]
	v_pk_add_f32 v[128:129], v[136:137], v[128:129] neg_lo:[0,1] neg_hi:[0,1]
	v_pk_add_f32 v[130:131], v[134:135], v[130:131] neg_lo:[0,1] neg_hi:[0,1]
	s_nop 0
	v_pk_add_f32 v[128:129], v[128:129], v[130:131]
	v_pk_add_f32 v[130:131], v[148:149], v[132:133]
	s_nop 0
	v_pk_add_f32 v[132:133], v[138:139], v[130:131]
	s_nop 0
	v_pk_add_f32 v[134:135], v[132:133], v[138:139] neg_lo:[0,1] neg_hi:[0,1]
	s_nop 0
	v_pk_add_f32 v[130:131], v[130:131], v[134:135] neg_lo:[0,1] neg_hi:[0,1]
	s_nop 0
	v_pk_add_f32 v[128:129], v[128:129], v[130:131]
	s_nop 0
	v_pk_add_f32 v[128:129], v[132:133], v[128:129]
	s_nop 0
	v_cndmask_b32_e32 v128, v235, v128, vcc
	v_cmp_neq_f32_e32 vcc, s3, v0
	s_nop 1
	v_cndmask_b32_e32 v129, v235, v129, vcc
	v_cmp_lt_f32_e64 vcc, |v0|, s14
	s_nop 1
	v_cndmask_b32_e32 v129, v129, v0, vcc
	v_cmp_lt_f32_e64 vcc, |v143|, s14
	s_lshl_b64 s[14:15], s[66:67], 4
	s_add_u32 s14, s44, s14
	v_cndmask_b32_e32 v128, v128, v143, vcc
	v_pk_add_f32 v[126:127], v[126:127], v[128:129] neg_lo:[0,1] neg_hi:[0,1]
	s_addc_u32 s15, s45, s15
	global_store_dwordx4 v1, v[124:127], s[14:15]
